# combo2 plus sc1 (write-through) on all 16-byte data stores of the main loop, to shorten the grid barriers L2 writeback
# speedup vs baseline: 1.0034x; 1.0034x over previous
.LBB0_146:
	v_lshl_or_b32 v146, s15, 7, v142
	v_lshl_add_u32 v144, s14, 8, v140
	v_ashrrev_i32_e32 v147, 31, v146
	v_mov_b64_e32 v[138:139], s[86:87]
	v_readlane_b32 s36, v255, 31
	s_andn2_b64 vcc, exec, s[4:5]
	v_readlane_b32 s37, v255, 32
	v_lshlrev_b64 v[148:149], 1, v[146:147]
	v_mul_f32_e32 v152, 0xbfb8aa3b, v126
	v_mul_f32_e32 v153, 0xbfb8aa3b, v127
	v_mul_f32_e32 v154, 0xbfb8aa3b, v128
	v_mul_f32_e32 v155, 0xbfb8aa3b, v129
	v_mul_f32_e32 v156, 0xbfb8aa3b, v118
	v_mul_f32_e32 v157, 0xbfb8aa3b, v119
	v_mul_f32_e32 v158, 0xbfb8aa3b, v120
	v_mul_f32_e32 v159, 0xbfb8aa3b, v121
	v_exp_f32_e32 v152, v152
	v_exp_f32_e32 v153, v153
	v_exp_f32_e32 v154, v154
	v_exp_f32_e32 v155, v155
	v_exp_f32_e32 v156, v156
	v_exp_f32_e32 v157, v157
	v_exp_f32_e32 v158, v158
	v_exp_f32_e32 v159, v159
	v_mad_i64_i32 v[150:151], s[14:15], v144, s72, v[138:139]
	v_add_f32_e32 v152, 1.0, v152
	v_add_f32_e32 v153, 1.0, v153
	v_add_f32_e32 v154, 1.0, v154
	v_add_f32_e32 v155, 1.0, v155
	v_add_f32_e32 v156, 1.0, v156
	v_add_f32_e32 v157, 1.0, v157
	v_add_f32_e32 v158, 1.0, v158
	v_add_f32_e32 v159, 1.0, v159
	v_rcp_f32_e32 v152, v152
	v_rcp_f32_e32 v153, v153
	v_rcp_f32_e32 v154, v154
	v_rcp_f32_e32 v155, v155
	v_rcp_f32_e32 v156, v156
	v_rcp_f32_e32 v157, v157
	v_rcp_f32_e32 v158, v158
	v_rcp_f32_e32 v159, v159
	v_lshl_add_u64 v[150:151], v[150:151], 0, v[148:149]
	v_mul_f32_e32 v126, v126, v152
	v_mul_f32_e32 v127, v127, v153
	v_mul_f32_e32 v128, v128, v154
	v_mul_f32_e32 v129, v129, v155
	v_mul_f32_e32 v118, v118, v156
	v_mul_f32_e32 v119, v119, v157
	v_mul_f32_e32 v120, v120, v158
	v_mul_f32_e32 v121, v121, v159
	v_mul_f32_e32 v126, v126, v122
	v_mul_f32_e32 v127, v127, v123
	v_mul_f32_e32 v128, v128, v124
	v_mul_f32_e32 v129, v129, v125
	v_mul_f32_e32 v118, v118, v114
	v_mul_f32_e32 v119, v119, v115
	v_mul_f32_e32 v120, v120, v116
	v_mul_f32_e32 v121, v121, v117
	v_cvt_pk_bf16_f32 v126, v126, v127
	v_cvt_pk_bf16_f32 v127, v128, v129
	v_cvt_pk_bf16_f32 v128, v118, v119
	v_cvt_pk_bf16_f32 v129, v120, v121
	global_store_dwordx4 v[150:151], v[126:129], off sc1
	v_mul_f32_e32 v152, 0xbfb8aa3b, v110
	v_mul_f32_e32 v153, 0xbfb8aa3b, v111
	v_mul_f32_e32 v154, 0xbfb8aa3b, v112
	v_mul_f32_e32 v155, 0xbfb8aa3b, v113
	v_mul_f32_e32 v156, 0xbfb8aa3b, v102
	v_mul_f32_e32 v157, 0xbfb8aa3b, v103
	v_mul_f32_e32 v158, 0xbfb8aa3b, v104
	v_mul_f32_e32 v159, 0xbfb8aa3b, v105
	v_or_b32_e32 v160, 16, v144
	v_exp_f32_e32 v152, v152
	v_exp_f32_e32 v153, v153
	v_exp_f32_e32 v154, v154
	v_exp_f32_e32 v155, v155
	v_exp_f32_e32 v156, v156
	v_exp_f32_e32 v157, v157
	v_exp_f32_e32 v158, v158
	v_exp_f32_e32 v159, v159
	v_mad_i64_i32 v[150:151], s[14:15], v160, s72, v[138:139]
	v_add_f32_e32 v152, 1.0, v152
	v_add_f32_e32 v153, 1.0, v153
	v_add_f32_e32 v154, 1.0, v154
	v_add_f32_e32 v155, 1.0, v155
	v_add_f32_e32 v156, 1.0, v156
	v_add_f32_e32 v157, 1.0, v157
	v_add_f32_e32 v158, 1.0, v158
	v_add_f32_e32 v159, 1.0, v159
	v_rcp_f32_e32 v152, v152
	v_rcp_f32_e32 v153, v153
	v_rcp_f32_e32 v154, v154
	v_rcp_f32_e32 v155, v155
	v_rcp_f32_e32 v156, v156
	v_rcp_f32_e32 v157, v157
	v_rcp_f32_e32 v158, v158
	v_rcp_f32_e32 v159, v159
	v_lshl_add_u64 v[150:151], v[150:151], 0, v[148:149]
	v_mul_f32_e32 v110, v110, v152
	v_mul_f32_e32 v111, v111, v153
	v_mul_f32_e32 v112, v112, v154
	v_mul_f32_e32 v113, v113, v155
	v_mul_f32_e32 v102, v102, v156
	v_mul_f32_e32 v103, v103, v157
	v_mul_f32_e32 v104, v104, v158
	v_mul_f32_e32 v105, v105, v159
	v_mul_f32_e32 v110, v110, v106
	v_mul_f32_e32 v111, v111, v107
	v_mul_f32_e32 v112, v112, v108
	v_mul_f32_e32 v113, v113, v109
	v_mul_f32_e32 v102, v102, v98
	v_mul_f32_e32 v103, v103, v99
	v_mul_f32_e32 v104, v104, v100
	v_mul_f32_e32 v105, v105, v101
	v_cvt_pk_bf16_f32 v110, v110, v111
	v_cvt_pk_bf16_f32 v111, v112, v113
	v_cvt_pk_bf16_f32 v112, v102, v103
	v_cvt_pk_bf16_f32 v113, v104, v105
	global_store_dwordx4 v[150:151], v[110:113], off sc1
	v_mul_f32_e32 v152, 0xbfb8aa3b, v94
	v_mul_f32_e32 v153, 0xbfb8aa3b, v95
	v_mul_f32_e32 v154, 0xbfb8aa3b, v96
	v_mul_f32_e32 v155, 0xbfb8aa3b, v97
	v_mul_f32_e32 v156, 0xbfb8aa3b, v86
	v_mul_f32_e32 v157, 0xbfb8aa3b, v87
	v_mul_f32_e32 v158, 0xbfb8aa3b, v88
	v_mul_f32_e32 v159, 0xbfb8aa3b, v89
	v_or_b32_e32 v160, 32, v144
	v_exp_f32_e32 v152, v152
	v_exp_f32_e32 v153, v153
	v_exp_f32_e32 v154, v154
	v_exp_f32_e32 v155, v155
	v_exp_f32_e32 v156, v156
	v_exp_f32_e32 v157, v157
	v_exp_f32_e32 v158, v158
	v_exp_f32_e32 v159, v159
	v_mad_i64_i32 v[150:151], s[14:15], v160, s72, v[138:139]
	v_add_f32_e32 v152, 1.0, v152
	v_add_f32_e32 v153, 1.0, v153
	v_add_f32_e32 v154, 1.0, v154
	v_add_f32_e32 v155, 1.0, v155
	v_add_f32_e32 v156, 1.0, v156
	v_add_f32_e32 v157, 1.0, v157
	v_add_f32_e32 v158, 1.0, v158
	v_add_f32_e32 v159, 1.0, v159
	v_rcp_f32_e32 v152, v152
	v_rcp_f32_e32 v153, v153
	v_rcp_f32_e32 v154, v154
	v_rcp_f32_e32 v155, v155
	v_rcp_f32_e32 v156, v156
	v_rcp_f32_e32 v157, v157
	v_rcp_f32_e32 v158, v158
	v_rcp_f32_e32 v159, v159
	v_lshl_add_u64 v[150:151], v[150:151], 0, v[148:149]
	v_mul_f32_e32 v94, v94, v152
	v_mul_f32_e32 v95, v95, v153
	v_mul_f32_e32 v96, v96, v154
	v_mul_f32_e32 v97, v97, v155
	v_mul_f32_e32 v86, v86, v156
	v_mul_f32_e32 v87, v87, v157
	v_mul_f32_e32 v88, v88, v158
	v_mul_f32_e32 v89, v89, v159
	v_mul_f32_e32 v94, v94, v90
	v_mul_f32_e32 v95, v95, v91
	v_mul_f32_e32 v96, v96, v92
	v_mul_f32_e32 v97, v97, v93
	v_mul_f32_e32 v86, v86, v82
	v_mul_f32_e32 v87, v87, v83
	v_mul_f32_e32 v88, v88, v84
	v_mul_f32_e32 v89, v89, v85
	v_cvt_pk_bf16_f32 v94, v94, v95
	v_cvt_pk_bf16_f32 v95, v96, v97
	v_cvt_pk_bf16_f32 v96, v86, v87
	v_cvt_pk_bf16_f32 v97, v88, v89
	global_store_dwordx4 v[150:151], v[94:97], off sc1
	v_mul_f32_e32 v152, 0xbfb8aa3b, v78
	v_mul_f32_e32 v153, 0xbfb8aa3b, v79
	v_mul_f32_e32 v154, 0xbfb8aa3b, v80
	v_mul_f32_e32 v155, 0xbfb8aa3b, v81
	v_mul_f32_e32 v156, 0xbfb8aa3b, v70
	v_mul_f32_e32 v157, 0xbfb8aa3b, v71
	v_mul_f32_e32 v158, 0xbfb8aa3b, v72
	v_mul_f32_e32 v159, 0xbfb8aa3b, v73
	v_or_b32_e32 v160, 48, v144
	v_exp_f32_e32 v152, v152
	v_exp_f32_e32 v153, v153
	v_exp_f32_e32 v154, v154
	v_exp_f32_e32 v155, v155
	v_exp_f32_e32 v156, v156
	v_exp_f32_e32 v157, v157
	v_exp_f32_e32 v158, v158
	v_exp_f32_e32 v159, v159
	v_mad_i64_i32 v[150:151], s[14:15], v160, s72, v[138:139]
	v_add_f32_e32 v152, 1.0, v152
	v_add_f32_e32 v153, 1.0, v153
	v_add_f32_e32 v154, 1.0, v154
	v_add_f32_e32 v155, 1.0, v155
	v_add_f32_e32 v156, 1.0, v156
	v_add_f32_e32 v157, 1.0, v157
	v_add_f32_e32 v158, 1.0, v158
	v_add_f32_e32 v159, 1.0, v159
	v_rcp_f32_e32 v152, v152
	v_rcp_f32_e32 v153, v153
	v_rcp_f32_e32 v154, v154
	v_rcp_f32_e32 v155, v155
	v_rcp_f32_e32 v156, v156
	v_rcp_f32_e32 v157, v157
	v_rcp_f32_e32 v158, v158
	v_rcp_f32_e32 v159, v159
	v_lshl_add_u64 v[150:151], v[150:151], 0, v[148:149]
	v_mul_f32_e32 v78, v78, v152
	v_mul_f32_e32 v79, v79, v153
	v_mul_f32_e32 v80, v80, v154
	v_mul_f32_e32 v81, v81, v155
	v_mul_f32_e32 v70, v70, v156
	v_mul_f32_e32 v71, v71, v157
	v_mul_f32_e32 v72, v72, v158
	v_mul_f32_e32 v73, v73, v159
	v_mul_f32_e32 v78, v78, v74
	v_mul_f32_e32 v79, v79, v75
	v_mul_f32_e32 v80, v80, v76
	v_mul_f32_e32 v81, v81, v77
	v_mul_f32_e32 v70, v70, v66
	v_mul_f32_e32 v71, v71, v67
	v_mul_f32_e32 v72, v72, v68
	v_mul_f32_e32 v73, v73, v69
	v_cvt_pk_bf16_f32 v78, v78, v79
	v_cvt_pk_bf16_f32 v79, v80, v81
	v_cvt_pk_bf16_f32 v80, v70, v71
	v_cvt_pk_bf16_f32 v81, v72, v73
	global_store_dwordx4 v[150:151], v[78:81], off sc1
	v_mul_f32_e32 v152, 0xbfb8aa3b, v62
	v_mul_f32_e32 v153, 0xbfb8aa3b, v63
	v_mul_f32_e32 v154, 0xbfb8aa3b, v64
	v_mul_f32_e32 v155, 0xbfb8aa3b, v65
	v_mul_f32_e32 v156, 0xbfb8aa3b, v54
	v_mul_f32_e32 v157, 0xbfb8aa3b, v55
	v_mul_f32_e32 v158, 0xbfb8aa3b, v56
	v_mul_f32_e32 v159, 0xbfb8aa3b, v57
	v_add_u32_e32 v160, 0x80, v144
	v_exp_f32_e32 v152, v152
	v_exp_f32_e32 v153, v153
	v_exp_f32_e32 v154, v154
	v_exp_f32_e32 v155, v155
	v_exp_f32_e32 v156, v156
	v_exp_f32_e32 v157, v157
	v_exp_f32_e32 v158, v158
	v_exp_f32_e32 v159, v159
	v_mad_i64_i32 v[150:151], s[14:15], v160, s72, v[138:139]
	v_add_f32_e32 v152, 1.0, v152
	v_add_f32_e32 v153, 1.0, v153
	v_add_f32_e32 v154, 1.0, v154
	v_add_f32_e32 v155, 1.0, v155
	v_add_f32_e32 v156, 1.0, v156
	v_add_f32_e32 v157, 1.0, v157
	v_add_f32_e32 v158, 1.0, v158
	v_add_f32_e32 v159, 1.0, v159
	v_rcp_f32_e32 v152, v152
	v_rcp_f32_e32 v153, v153
	v_rcp_f32_e32 v154, v154
	v_rcp_f32_e32 v155, v155
	v_rcp_f32_e32 v156, v156
	v_rcp_f32_e32 v157, v157
	v_rcp_f32_e32 v158, v158
	v_rcp_f32_e32 v159, v159
	v_lshl_add_u64 v[150:151], v[150:151], 0, v[148:149]
	v_mul_f32_e32 v62, v62, v152
	v_mul_f32_e32 v63, v63, v153
	v_mul_f32_e32 v64, v64, v154
	v_mul_f32_e32 v65, v65, v155
	v_mul_f32_e32 v54, v54, v156
	v_mul_f32_e32 v55, v55, v157
	v_mul_f32_e32 v56, v56, v158
	v_mul_f32_e32 v57, v57, v159
	v_mul_f32_e32 v62, v62, v58
	v_mul_f32_e32 v63, v63, v59
	v_mul_f32_e32 v64, v64, v60
	v_mul_f32_e32 v65, v65, v61
	v_mul_f32_e32 v54, v54, v50
	v_mul_f32_e32 v55, v55, v51
	v_mul_f32_e32 v56, v56, v52
	v_mul_f32_e32 v57, v57, v53
	v_cvt_pk_bf16_f32 v62, v62, v63
	v_cvt_pk_bf16_f32 v63, v64, v65
	v_cvt_pk_bf16_f32 v64, v54, v55
	v_cvt_pk_bf16_f32 v65, v56, v57
	global_store_dwordx4 v[150:151], v[62:65], off sc1
	v_mul_f32_e32 v152, 0xbfb8aa3b, v46
	v_mul_f32_e32 v153, 0xbfb8aa3b, v47
	v_mul_f32_e32 v154, 0xbfb8aa3b, v48
	v_mul_f32_e32 v155, 0xbfb8aa3b, v49
	v_mul_f32_e32 v156, 0xbfb8aa3b, v38
	v_mul_f32_e32 v157, 0xbfb8aa3b, v39
	v_mul_f32_e32 v158, 0xbfb8aa3b, v40
	v_mul_f32_e32 v159, 0xbfb8aa3b, v41
	v_add_u32_e32 v160, 0x90, v144
	v_exp_f32_e32 v152, v152
	v_exp_f32_e32 v153, v153
	v_exp_f32_e32 v154, v154
	v_exp_f32_e32 v155, v155
	v_exp_f32_e32 v156, v156
	v_exp_f32_e32 v157, v157
	v_exp_f32_e32 v158, v158
	v_exp_f32_e32 v159, v159
	v_mad_i64_i32 v[150:151], s[14:15], v160, s72, v[138:139]
	v_add_f32_e32 v152, 1.0, v152
	v_add_f32_e32 v153, 1.0, v153
	v_add_f32_e32 v154, 1.0, v154
	v_add_f32_e32 v155, 1.0, v155
	v_add_f32_e32 v156, 1.0, v156
	v_add_f32_e32 v157, 1.0, v157
	v_add_f32_e32 v158, 1.0, v158
	v_add_f32_e32 v159, 1.0, v159
	v_rcp_f32_e32 v152, v152
	v_rcp_f32_e32 v153, v153
	v_rcp_f32_e32 v154, v154
	v_rcp_f32_e32 v155, v155
	v_rcp_f32_e32 v156, v156
	v_rcp_f32_e32 v157, v157
	v_rcp_f32_e32 v158, v158
	v_rcp_f32_e32 v159, v159
	v_lshl_add_u64 v[150:151], v[150:151], 0, v[148:149]
	v_mul_f32_e32 v46, v46, v152
	v_mul_f32_e32 v47, v47, v153
	v_mul_f32_e32 v48, v48, v154
	v_mul_f32_e32 v49, v49, v155
	v_mul_f32_e32 v38, v38, v156
	v_mul_f32_e32 v39, v39, v157
	v_mul_f32_e32 v40, v40, v158
	v_mul_f32_e32 v41, v41, v159
	v_mul_f32_e32 v46, v46, v42
	v_mul_f32_e32 v47, v47, v43
	v_mul_f32_e32 v48, v48, v44
	v_mul_f32_e32 v49, v49, v45
	v_mul_f32_e32 v38, v38, v34
	v_mul_f32_e32 v39, v39, v35
	v_mul_f32_e32 v40, v40, v36
	v_mul_f32_e32 v41, v41, v37
	v_cvt_pk_bf16_f32 v46, v46, v47
	v_cvt_pk_bf16_f32 v47, v48, v49
	v_cvt_pk_bf16_f32 v48, v38, v39
	v_cvt_pk_bf16_f32 v49, v40, v41
	global_store_dwordx4 v[150:151], v[46:49], off sc1
	v_mul_f32_e32 v152, 0xbfb8aa3b, v30
	v_mul_f32_e32 v153, 0xbfb8aa3b, v31
	v_mul_f32_e32 v154, 0xbfb8aa3b, v32
	v_mul_f32_e32 v155, 0xbfb8aa3b, v33
	v_mul_f32_e32 v156, 0xbfb8aa3b, v22
	v_mul_f32_e32 v157, 0xbfb8aa3b, v23
	v_mul_f32_e32 v158, 0xbfb8aa3b, v24
	v_mul_f32_e32 v159, 0xbfb8aa3b, v25
	v_add_u32_e32 v160, 0xa0, v144
	v_exp_f32_e32 v152, v152
	v_exp_f32_e32 v153, v153
	v_exp_f32_e32 v154, v154
	v_exp_f32_e32 v155, v155
	v_exp_f32_e32 v156, v156
	v_exp_f32_e32 v157, v157
	v_exp_f32_e32 v158, v158
	v_exp_f32_e32 v159, v159
	v_mad_i64_i32 v[150:151], s[14:15], v160, s72, v[138:139]
	v_add_f32_e32 v152, 1.0, v152
	v_add_f32_e32 v153, 1.0, v153
	v_add_f32_e32 v154, 1.0, v154
	v_add_f32_e32 v155, 1.0, v155
	v_add_f32_e32 v156, 1.0, v156
	v_add_f32_e32 v157, 1.0, v157
	v_add_f32_e32 v158, 1.0, v158
	v_add_f32_e32 v159, 1.0, v159
	v_rcp_f32_e32 v152, v152
	v_rcp_f32_e32 v153, v153
	v_rcp_f32_e32 v154, v154
	v_rcp_f32_e32 v155, v155
	v_rcp_f32_e32 v156, v156
	v_rcp_f32_e32 v157, v157
	v_rcp_f32_e32 v158, v158
	v_rcp_f32_e32 v159, v159
	v_lshl_add_u64 v[150:151], v[150:151], 0, v[148:149]
	v_mul_f32_e32 v30, v30, v152
	v_mul_f32_e32 v31, v31, v153
	v_mul_f32_e32 v32, v32, v154
	v_mul_f32_e32 v33, v33, v155
	v_mul_f32_e32 v22, v22, v156
	v_mul_f32_e32 v23, v23, v157
	v_mul_f32_e32 v24, v24, v158
	v_mul_f32_e32 v25, v25, v159
	v_mul_f32_e32 v30, v30, v26
	v_mul_f32_e32 v31, v31, v27
	v_mul_f32_e32 v32, v32, v28
	v_mul_f32_e32 v33, v33, v29
	v_mul_f32_e32 v22, v22, v18
	v_mul_f32_e32 v23, v23, v19
	v_mul_f32_e32 v24, v24, v20
	v_mul_f32_e32 v25, v25, v21
	v_cvt_pk_bf16_f32 v30, v30, v31
	v_cvt_pk_bf16_f32 v31, v32, v33
	v_cvt_pk_bf16_f32 v32, v22, v23
	v_cvt_pk_bf16_f32 v33, v24, v25
	global_store_dwordx4 v[150:151], v[30:33], off sc1
	v_mul_f32_e32 v152, 0xbfb8aa3b, v14
	v_mul_f32_e32 v153, 0xbfb8aa3b, v15
	v_mul_f32_e32 v154, 0xbfb8aa3b, v16
	v_mul_f32_e32 v155, 0xbfb8aa3b, v17
	v_mul_f32_e32 v156, 0xbfb8aa3b, v6
	v_mul_f32_e32 v157, 0xbfb8aa3b, v7
	v_mul_f32_e32 v158, 0xbfb8aa3b, v8
	v_mul_f32_e32 v159, 0xbfb8aa3b, v9
	v_add_u32_e32 v160, 0xb0, v144
	v_exp_f32_e32 v152, v152
	v_exp_f32_e32 v153, v153
	v_exp_f32_e32 v154, v154
	v_exp_f32_e32 v155, v155
	v_exp_f32_e32 v156, v156
	v_exp_f32_e32 v157, v157
	v_exp_f32_e32 v158, v158
	v_exp_f32_e32 v159, v159
	v_mad_i64_i32 v[150:151], s[14:15], v160, s72, v[138:139]
	v_add_f32_e32 v152, 1.0, v152
	v_add_f32_e32 v153, 1.0, v153
	v_add_f32_e32 v154, 1.0, v154
	v_add_f32_e32 v155, 1.0, v155
	v_add_f32_e32 v156, 1.0, v156
	v_add_f32_e32 v157, 1.0, v157
	v_add_f32_e32 v158, 1.0, v158
	v_add_f32_e32 v159, 1.0, v159
	v_rcp_f32_e32 v152, v152
	v_rcp_f32_e32 v153, v153
	v_rcp_f32_e32 v154, v154
	v_rcp_f32_e32 v155, v155
	v_rcp_f32_e32 v156, v156
	v_rcp_f32_e32 v157, v157
	v_rcp_f32_e32 v158, v158
	v_rcp_f32_e32 v159, v159
	v_lshl_add_u64 v[150:151], v[150:151], 0, v[148:149]
	v_mul_f32_e32 v14, v14, v152
	v_mul_f32_e32 v15, v15, v153
	v_mul_f32_e32 v16, v16, v154
	v_mul_f32_e32 v17, v17, v155
	v_mul_f32_e32 v6, v6, v156
	v_mul_f32_e32 v7, v7, v157
	v_mul_f32_e32 v8, v8, v158
	v_mul_f32_e32 v9, v9, v159
	v_mul_f32_e32 v14, v14, v10
	v_mul_f32_e32 v15, v15, v11
	v_mul_f32_e32 v16, v16, v12
	v_mul_f32_e32 v17, v17, v13
	v_mul_f32_e32 v6, v6, v2
	v_mul_f32_e32 v7, v7, v3
	v_mul_f32_e32 v8, v8, v4
	v_mul_f32_e32 v9, v9, v5
	v_cvt_pk_bf16_f32 v14, v14, v15
	v_cvt_pk_bf16_f32 v15, v16, v17
	v_cvt_pk_bf16_f32 v16, v6, v7
	v_cvt_pk_bf16_f32 v17, v8, v9
	global_store_dwordx4 v[150:151], v[14:17], off sc1
	s_mov_b64 s[14:15], -1
	s_cbranch_vccnz .LBB0_139
	s_andn2_b64 vcc, exec, s[0:1]
	s_cbranch_vccnz .LBB0_138
	s_barrier
	s_branch .LBB0_138

.LBB0_250:
	v_cndmask_b32_e64 v0, v190, v192, s[0:1]
	v_cndmask_b32_e64 v10, v193, v194, s[0:1]
	s_mov_b64 s[26:27], -1
	s_and_b64 vcc, exec, s[8:9]
	v_lshlrev_b32_e32 v0, 1, v0
	v_lshlrev_b32_e32 v184, 1, v10
	s_cbranch_vccnz .LBB0_252
	v_lshl_add_u64 v[14:15], v[188:189], 0, v[0:1]
	v_mov_b32_e32 v185, v1
	v_cvt_pk_bf16_f32 v10, v166, v167
	v_cvt_pk_bf16_f32 v11, v168, v169
	v_cvt_pk_bf16_f32 v12, v162, v163
	v_cvt_pk_bf16_f32 v13, v164, v165
	global_store_dwordx4 v[14:15], v[10:13], off sc1
	v_lshl_add_u64 v[14:15], v[188:189], 0, v[184:185]
	s_mov_b64 s[26:27], 0
	v_cvt_pk_bf16_f32 v10, v158, v159
	v_cvt_pk_bf16_f32 v11, v160, v161
	v_cvt_pk_bf16_f32 v12, v154, v155
	v_cvt_pk_bf16_f32 v13, v156, v157
	global_store_dwordx4 v[14:15], v[10:13], off sc1

.LBB0_312:
	s_add_i32 s0, s47, -3
	v_mov_b32_e32 v0, 0x2100000
	v_ashrrev_i32_e32 v183, 31, v182
	v_mad_u64_u32 v[8:9], s[0:1], s0, v0, v[176:177]
	v_lshlrev_b64 v[2:3], 9, v[182:183]
	v_lshl_add_u64 v[2:3], v[8:9], 0, v[2:3]
	v_cvt_pk_bf16_f32 v4, v142, v143
	v_cvt_pk_bf16_f32 v5, v144, v145
	v_cvt_pk_bf16_f32 v6, v138, v139
	v_cvt_pk_bf16_f32 v7, v140, v141
	global_store_dwordx4 v[2:3], v[4:7], off sc1
	s_mov_b64 s[0:1], 0x12000
	s_nop 0
	v_cvt_pk_bf16_f32 v4, v130, v131
	v_cvt_pk_bf16_f32 v5, v132, v133
	v_cvt_pk_bf16_f32 v6, v122, v123
	v_cvt_pk_bf16_f32 v7, v124, v125
	global_store_dwordx4 v[2:3], v[4:7], off offset:256 sc1
	s_nop 1
	v_or_b32_e32 v4, 16, v182
	v_ashrrev_i32_e32 v5, 31, v4
	v_lshlrev_b64 v[4:5], 9, v[4:5]
	v_lshl_add_u64 v[10:11], v[8:9], 0, v[4:5]
	v_cvt_pk_bf16_f32 v4, v134, v135
	v_cvt_pk_bf16_f32 v5, v136, v137
	v_cvt_pk_bf16_f32 v6, v126, v127
	v_cvt_pk_bf16_f32 v7, v128, v129
	global_store_dwordx4 v[10:11], v[4:7], off sc1
	s_nop 1
	v_cvt_pk_bf16_f32 v4, v114, v115
	v_cvt_pk_bf16_f32 v5, v116, v117
	v_cvt_pk_bf16_f32 v6, v106, v107
	v_cvt_pk_bf16_f32 v7, v108, v109
	global_store_dwordx4 v[10:11], v[4:7], off offset:256 sc1
	s_nop 1
	v_or_b32_e32 v4, 32, v182
	v_ashrrev_i32_e32 v5, 31, v4
	v_lshlrev_b64 v[4:5], 9, v[4:5]
	v_lshl_add_u64 v[10:11], v[8:9], 0, v[4:5]
	v_cvt_pk_bf16_f32 v4, v118, v119
	v_cvt_pk_bf16_f32 v5, v120, v121
	v_cvt_pk_bf16_f32 v6, v110, v111
	v_cvt_pk_bf16_f32 v7, v112, v113
	global_store_dwordx4 v[10:11], v[4:7], off sc1
	s_nop 1
	v_cvt_pk_bf16_f32 v4, v98, v99
	v_cvt_pk_bf16_f32 v5, v100, v101
	v_cvt_pk_bf16_f32 v6, v90, v91
	v_cvt_pk_bf16_f32 v7, v92, v93
	global_store_dwordx4 v[10:11], v[4:7], off offset:256 sc1
	v_add_co_u32_e32 v10, vcc, s33, v2
	s_nop 0
	v_or_b32_e32 v4, 48, v182
	v_ashrrev_i32_e32 v5, 31, v4
	v_lshlrev_b64 v[4:5], 9, v[4:5]
	v_lshl_add_u64 v[8:9], v[8:9], 0, v[4:5]
	v_cvt_pk_bf16_f32 v4, v102, v103
	v_cvt_pk_bf16_f32 v5, v104, v105
	v_cvt_pk_bf16_f32 v6, v94, v95
	v_cvt_pk_bf16_f32 v7, v96, v97
	global_store_dwordx4 v[8:9], v[4:7], off sc1
	v_addc_co_u32_e32 v11, vcc, 0, v3, vcc
	s_nop 0
	v_cvt_pk_bf16_f32 v4, v86, v87
	v_cvt_pk_bf16_f32 v5, v88, v89
	v_cvt_pk_bf16_f32 v6, v82, v83
	v_cvt_pk_bf16_f32 v7, v84, v85
	global_store_dwordx4 v[8:9], v[4:7], off offset:256 sc1
	v_lshl_add_u64 v[8:9], v[2:3], 0, s[38:39]
	s_nop 0
	v_cvt_pk_bf16_f32 v4, v78, v79
	v_cvt_pk_bf16_f32 v5, v80, v81
	v_cvt_pk_bf16_f32 v6, v74, v75
	v_cvt_pk_bf16_f32 v7, v76, v77
	global_store_dwordx4 v[10:11], v[4:7], off sc1
	s_nop 1
	v_cvt_pk_bf16_f32 v4, v66, v67
	v_cvt_pk_bf16_f32 v5, v68, v69
	v_cvt_pk_bf16_f32 v6, v58, v59
	v_cvt_pk_bf16_f32 v7, v60, v61
	global_store_dwordx4 v[8:9], v[4:7], off offset:256 sc1
	v_lshl_add_u64 v[8:9], v[2:3], 0, s[0:1]
	s_mov_b32 s0, 0x12000
	v_add_co_u32_e32 v10, vcc, s0, v2
	v_cvt_pk_bf16_f32 v4, v70, v71
	v_cvt_pk_bf16_f32 v5, v72, v73
	v_cvt_pk_bf16_f32 v6, v62, v63
	v_cvt_pk_bf16_f32 v7, v64, v65
	s_nop 1
	v_addc_co_u32_e32 v11, vcc, 0, v3, vcc
	s_mov_b64 s[0:1], 0x14000
	global_store_dwordx4 v[10:11], v[4:7], off sc1
	s_nop 1
	v_cvt_pk_bf16_f32 v4, v50, v51
	v_cvt_pk_bf16_f32 v5, v52, v53
	v_cvt_pk_bf16_f32 v6, v42, v43
	v_cvt_pk_bf16_f32 v7, v44, v45
	global_store_dwordx4 v[8:9], v[4:7], off offset:256 sc1
	v_lshl_add_u64 v[8:9], v[2:3], 0, s[0:1]
	s_mov_b32 s0, 0x14000
	v_add_co_u32_e32 v10, vcc, s0, v2
	v_cvt_pk_bf16_f32 v4, v54, v55
	v_cvt_pk_bf16_f32 v5, v56, v57
	v_cvt_pk_bf16_f32 v6, v46, v47
	v_cvt_pk_bf16_f32 v7, v48, v49
	s_nop 1
	v_addc_co_u32_e32 v11, vcc, 0, v3, vcc
	s_mov_b64 s[0:1], 0x16000
	global_store_dwordx4 v[10:11], v[4:7], off sc1
	s_nop 1
	v_cvt_pk_bf16_f32 v4, v34, v35
	v_cvt_pk_bf16_f32 v5, v36, v37
	v_cvt_pk_bf16_f32 v6, v26, v27
	v_cvt_pk_bf16_f32 v7, v28, v29
	global_store_dwordx4 v[8:9], v[4:7], off offset:256 sc1
	v_lshl_add_u64 v[8:9], v[2:3], 0, s[0:1]
	s_mov_b32 s0, 0x16000
	v_add_co_u32_e32 v2, vcc, s0, v2
	v_cvt_pk_bf16_f32 v4, v38, v39
	v_cvt_pk_bf16_f32 v5, v40, v41
	v_cvt_pk_bf16_f32 v6, v30, v31
	v_cvt_pk_bf16_f32 v7, v32, v33
	s_nop 1
	v_addc_co_u32_e32 v3, vcc, 0, v3, vcc
	global_store_dwordx4 v[2:3], v[4:7], off sc1
	v_cvt_pk_bf16_f32 v2, v22, v23
	v_cvt_pk_bf16_f32 v3, v24, v25
	s_nop 1
	v_cvt_pk_bf16_f32 v4, v18, v19
	v_cvt_pk_bf16_f32 v5, v20, v21
	global_store_dwordx4 v[8:9], v[2:5], off offset:256 sc1
	s_andn2_b64 vcc, exec, s[6:7]
	s_mov_b64 s[0:1], -1
	s_cbranch_vccnz .LBB0_229

.LBB0_317:
	v_lshl_add_u64 v[14:15], v[2:3], 0, v[0:1]
	v_mov_b32_e32 v185, v1
	v_cvt_pk_bf16_f32 v10, v166, v167
	v_cvt_pk_bf16_f32 v11, v168, v169
	v_cvt_pk_bf16_f32 v12, v162, v163
	v_cvt_pk_bf16_f32 v13, v164, v165
	global_store_dwordx4 v[14:15], v[10:13], off sc1
	v_lshl_add_u64 v[14:15], v[2:3], 0, v[184:185]
	s_nop 0
	v_cvt_pk_bf16_f32 v10, v158, v159
	v_cvt_pk_bf16_f32 v11, v160, v161
	v_cvt_pk_bf16_f32 v12, v154, v155
	v_cvt_pk_bf16_f32 v13, v156, v157
	global_store_dwordx4 v[14:15], v[10:13], off sc1
	s_cbranch_execz .LBB0_261
	s_branch .LBB0_262

.LBB0_323:
	v_lshl_add_u64 v[14:15], v[166:167], 0, v[0:1]
	v_mov_b32_e32 v185, v1
	v_cvt_pk_bf16_f32 v10, v162, v163
	v_cvt_pk_bf16_f32 v11, v164, v165
	v_cvt_pk_bf16_f32 v12, v158, v159
	v_cvt_pk_bf16_f32 v13, v160, v161
	global_store_dwordx4 v[14:15], v[10:13], off sc1
	v_lshl_add_u64 v[14:15], v[166:167], 0, v[184:185]
	s_nop 0
	v_cvt_pk_bf16_f32 v10, v154, v155
	v_cvt_pk_bf16_f32 v11, v156, v157
	v_cvt_pk_bf16_f32 v12, v2, v3
	v_cvt_pk_bf16_f32 v13, v4, v5
	global_store_dwordx4 v[14:15], v[10:13], off sc1
	s_cbranch_execz .LBB0_277
	s_branch .LBB0_278

.LBB0_325:
	v_lshl_add_u64 v[10:11], v[168:169], 0, v[0:1]
	v_mov_b32_e32 v185, v1
	v_cvt_pk_bf16_f32 v2, v162, v163
	v_cvt_pk_bf16_f32 v3, v164, v165
	v_cvt_pk_bf16_f32 v4, v158, v159
	v_cvt_pk_bf16_f32 v5, v160, v161
	global_store_dwordx4 v[10:11], v[2:5], off sc1
	v_lshl_add_u64 v[10:11], v[168:169], 0, v[184:185]
	s_nop 0
	v_cvt_pk_bf16_f32 v2, v154, v155
	v_cvt_pk_bf16_f32 v3, v156, v157
	v_cvt_pk_bf16_f32 v4, v150, v151
	v_cvt_pk_bf16_f32 v5, v152, v153
	global_store_dwordx4 v[10:11], v[2:5], off sc1
	s_cbranch_execz .LBB0_286
	s_branch .LBB0_287

.LBB0_328:
	v_lshl_add_u64 v[10:11], v[6:7], 0, v[0:1]
	v_mov_b32_e32 v185, v1
	v_cvt_pk_bf16_f32 v2, v162, v163
	v_cvt_pk_bf16_f32 v3, v164, v165
	v_cvt_pk_bf16_f32 v4, v158, v159
	v_cvt_pk_bf16_f32 v5, v160, v161
	global_store_dwordx4 v[10:11], v[2:5], off sc1
	v_lshl_add_u64 v[10:11], v[6:7], 0, v[184:185]
	s_nop 0
	v_cvt_pk_bf16_f32 v2, v154, v155
	v_cvt_pk_bf16_f32 v3, v156, v157
	v_cvt_pk_bf16_f32 v4, v150, v151
	v_cvt_pk_bf16_f32 v5, v152, v153
	global_store_dwordx4 v[10:11], v[2:5], off sc1
	s_cbranch_execz .LBB0_294
	s_branch .LBB0_295

.LBB0_334:
	v_lshl_add_u64 v[10:11], v[162:163], 0, v[0:1]
	v_mov_b32_e32 v185, v1
	v_cvt_pk_bf16_f32 v2, v158, v159
	v_cvt_pk_bf16_f32 v3, v160, v161
	v_cvt_pk_bf16_f32 v4, v154, v155
	v_cvt_pk_bf16_f32 v5, v156, v157
	global_store_dwordx4 v[10:11], v[2:5], off sc1
	v_lshl_add_u64 v[10:11], v[162:163], 0, v[184:185]
	s_nop 0
	v_cvt_pk_bf16_f32 v2, v150, v151
	v_cvt_pk_bf16_f32 v3, v152, v153
	v_cvt_pk_bf16_f32 v4, v6, v7
	v_cvt_pk_bf16_f32 v5, v8, v9
	global_store_dwordx4 v[10:11], v[2:5], off sc1
	s_cbranch_execz .LBB0_310
	s_branch .LBB0_311

.LBB0_390:
	s_waitcnt lgkmcnt(0)
	s_barrier
	ds_read_b128 v[22:25], v195
	v_add_u32_e32 v26, s18, v160
	v_ashrrev_i32_e32 v27, 31, v26
	v_lshlrev_b64 v[26:27], 10, v[26:27]
	v_lshl_add_u64 v[26:27], v[106:107], 0, v[26:27]
	s_waitcnt lgkmcnt(0)
	global_store_dwordx4 v[26:27], v[22:25], off sc1
	ds_read_b128 v[22:25], v196
	v_add_u32_e32 v26, s18, v183
	v_ashrrev_i32_e32 v27, 31, v26
	v_lshlrev_b64 v[26:27], 10, v[26:27]
	v_lshl_add_u64 v[26:27], v[106:107], 0, v[26:27]
	s_waitcnt lgkmcnt(0)
	global_store_dwordx4 v[26:27], v[22:25], off sc1
	ds_read_b128 v[22:25], v197
	v_add_u32_e32 v26, s18, v184
	v_ashrrev_i32_e32 v27, 31, v26
	v_lshlrev_b64 v[26:27], 10, v[26:27]
	v_lshl_add_u64 v[26:27], v[106:107], 0, v[26:27]
	s_waitcnt lgkmcnt(0)
	global_store_dwordx4 v[26:27], v[22:25], off sc1
	ds_read_b128 v[22:25], v198
	v_add_u32_e32 v26, s18, v185
	v_ashrrev_i32_e32 v27, 31, v26
	v_lshlrev_b64 v[26:27], 10, v[26:27]
	v_lshl_add_u64 v[26:27], v[106:107], 0, v[26:27]
	s_waitcnt lgkmcnt(0)
	global_store_dwordx4 v[26:27], v[22:25], off sc1
	ds_read_b128 v[22:25], v199
	v_add_u32_e32 v26, s18, v186
	v_ashrrev_i32_e32 v27, 31, v26
	v_lshlrev_b64 v[26:27], 10, v[26:27]
	v_lshl_add_u64 v[26:27], v[106:107], 0, v[26:27]
	s_waitcnt lgkmcnt(0)
	global_store_dwordx4 v[26:27], v[22:25], off sc1
	ds_read_b128 v[22:25], v200
	v_add_u32_e32 v26, s18, v187
	v_ashrrev_i32_e32 v27, 31, v26
	v_lshlrev_b64 v[26:27], 10, v[26:27]
	v_lshl_add_u64 v[26:27], v[106:107], 0, v[26:27]
	s_waitcnt lgkmcnt(0)
	global_store_dwordx4 v[26:27], v[22:25], off sc1
	ds_read_b128 v[22:25], v201
	v_add_u32_e32 v26, s18, v188
	v_ashrrev_i32_e32 v27, 31, v26
	v_lshlrev_b64 v[26:27], 10, v[26:27]
	v_lshl_add_u64 v[26:27], v[106:107], 0, v[26:27]
	s_waitcnt lgkmcnt(0)
	global_store_dwordx4 v[26:27], v[22:25], off sc1
	ds_read_b128 v[22:25], v202
	v_add_u32_e32 v26, s18, v189
	v_ashrrev_i32_e32 v27, 31, v26
	v_lshlrev_b64 v[26:27], 10, v[26:27]
	v_lshl_add_u64 v[26:27], v[106:107], 0, v[26:27]
	s_waitcnt lgkmcnt(0)
	global_store_dwordx4 v[26:27], v[22:25], off sc1
	s_waitcnt lgkmcnt(0)
	s_barrier
	s_add_i32 s2, s2, s24
	s_cmpk_gt_i32 s2, 0x41f
	s_cbranch_scc1 .LBB0_419

.LBB0_478:
	s_or_b64 exec, exec, s[0:1]
	s_waitcnt lgkmcnt(0)
	ds_read_b128 v[34:37], v50 offset:49280
	ds_read_b128 v[38:41], v50 offset:49312
	s_lshl_b64 s[0:1], s[10:11], 1
	s_add_u32 s0, s76, s0
	s_addc_u32 s1, s77, s1
	s_waitcnt lgkmcnt(1)
	v_rcp_f32_e32 v42, v34
	s_add_u32 s3, s0, s6
	v_rcp_f32_e32 v43, v35
	s_addc_u32 s4, s1, s7
	s_lshl_b32 s0, s2, 12
	v_rcp_f32_e32 v44, v36
	v_rcp_f32_e32 v45, v37
	s_waitcnt lgkmcnt(0)
	v_rcp_f32_e32 v46, v38
	ds_read_b128 v[34:37], v50 offset:49344
	v_rcp_f32_e32 v47, v39
	v_rcp_f32_e32 v48, v40
	v_rcp_f32_e32 v49, v41
	ds_read_b128 v[38:41], v50 offset:49376
	s_add_i32 s2, s0, 0
	v_lshlrev_b32_e32 v50, 9, v196
	v_lshlrev_b32_e32 v51, 1, v195
	v_mul_f32_e32 v2, v2, v42
	v_add3_u32 v50, s2, v50, v51
	v_cvt_pk_bf16_f32 v2, v2, s0
	ds_write_b16 v50, v2 offset:51264
	v_mul_f32_e32 v2, v19, v43
	v_cvt_pk_bf16_f32 v2, v2, s0
	ds_write_b16 v50, v2 offset:51328
	v_mul_f32_e32 v2, v3, v43
	v_cvt_pk_bf16_f32 v2, v2, s0
	ds_write_b16 v50, v2 offset:51392
	v_mul_f32_e32 v2, v20, v44
	v_cvt_pk_bf16_f32 v2, v2, s0
	ds_write_b16 v50, v2 offset:51456
	v_mul_f32_e32 v2, v4, v44
	v_cvt_pk_bf16_f32 v2, v2, s0
	ds_write_b16 v50, v2 offset:51520
	v_mul_f32_e32 v2, v21, v45
	v_cvt_pk_bf16_f32 v2, v2, s0
	ds_write_b16 v50, v2 offset:51584
	v_mul_f32_e32 v2, v5, v45
	v_cvt_pk_bf16_f32 v2, v2, s0
	ds_write_b16 v50, v2 offset:51648
	v_mul_f32_e32 v2, v22, v46
	v_cvt_pk_bf16_f32 v2, v2, s0
	ds_write_b16 v50, v2 offset:52224
	v_mul_f32_e32 v2, v6, v46
	v_cvt_pk_bf16_f32 v2, v2, s0
	ds_write_b16 v50, v2 offset:52288
	v_mul_f32_e32 v2, v23, v47
	v_cvt_pk_bf16_f32 v2, v2, s0
	ds_write_b16 v50, v2 offset:52352
	v_mul_f32_e32 v2, v7, v47
	v_cvt_pk_bf16_f32 v2, v2, s0
	ds_write_b16 v50, v2 offset:52416
	v_mul_f32_e32 v2, v24, v48
	v_cvt_pk_bf16_f32 v2, v2, s0
	ds_write_b16 v50, v2 offset:52480
	v_mul_f32_e32 v2, v8, v48
	v_cvt_pk_bf16_f32 v2, v2, s0
	s_waitcnt lgkmcnt(13)
	v_rcp_f32_e32 v34, v34
	ds_write_b16 v50, v2 offset:52544
	v_mul_f32_e32 v2, v25, v49
	v_cvt_pk_bf16_f32 v2, v2, s0
	ds_write_b16 v50, v2 offset:52608
	v_mul_f32_e32 v2, v9, v49
	v_cvt_pk_bf16_f32 v2, v2, s0
	v_rcp_f32_e32 v35, v35
	ds_write_b16 v50, v2 offset:52672
	v_mul_f32_e32 v2, v26, v34
	v_cvt_pk_bf16_f32 v2, v2, s0
	ds_write_b16 v50, v2 offset:53248
	v_mul_f32_e32 v2, v10, v34
	v_cvt_pk_bf16_f32 v2, v2, s0
	v_rcp_f32_e32 v36, v36
	ds_write_b16 v50, v2 offset:53312
	v_mul_f32_e32 v2, v27, v35
	v_cvt_pk_bf16_f32 v2, v2, s0
	ds_write_b16 v50, v2 offset:53376
	v_mul_f32_e32 v2, v11, v35
	v_cvt_pk_bf16_f32 v2, v2, s0
	v_rcp_f32_e32 v37, v37
	ds_write_b16 v50, v2 offset:53440
	v_mul_f32_e32 v2, v28, v36
	v_cvt_pk_bf16_f32 v2, v2, s0
	ds_write_b16 v50, v2 offset:53504
	v_mul_f32_e32 v2, v12, v36
	v_cvt_pk_bf16_f32 v2, v2, s0
	s_waitcnt lgkmcnt(14)
	v_rcp_f32_e32 v38, v38
	ds_write_b16 v50, v2 offset:53568
	v_mul_f32_e32 v2, v29, v37
	v_cvt_pk_bf16_f32 v2, v2, s0
	ds_write_b16 v50, v2 offset:53632
	v_mul_f32_e32 v2, v13, v37
	v_cvt_pk_bf16_f32 v2, v2, s0
	v_rcp_f32_e32 v39, v39
	ds_write_b16 v50, v2 offset:53696
	v_mul_f32_e32 v2, v30, v38
	v_cvt_pk_bf16_f32 v2, v2, s0
	ds_write_b16 v50, v2 offset:54272
	v_mul_f32_e32 v2, v14, v38
	v_cvt_pk_bf16_f32 v2, v2, s0
	v_rcp_f32_e32 v40, v40
	ds_write_b16 v50, v2 offset:54336
	v_mul_f32_e32 v2, v31, v39
	v_cvt_pk_bf16_f32 v2, v2, s0
	ds_write_b16 v50, v2 offset:54400
	v_mul_f32_e32 v2, v15, v39
	v_cvt_pk_bf16_f32 v2, v2, s0
	v_rcp_f32_e32 v41, v41
	ds_write_b16 v50, v2 offset:54464
	v_mul_f32_e32 v2, v32, v40
	v_cvt_pk_bf16_f32 v2, v2, s0
	ds_write_b16 v50, v2 offset:54528
	v_mul_f32_e32 v2, v16, v40
	v_cvt_pk_bf16_f32 v2, v2, s0
	ds_write_b16 v50, v2 offset:54592
	v_mul_f32_e32 v2, v33, v41
	v_cvt_pk_bf16_f32 v2, v2, s0
	v_mul_f32_e32 v18, v18, v42
	ds_write_b16 v50, v2 offset:54656
	v_mul_f32_e32 v2, v17, v41
	v_cvt_pk_bf16_f32 v18, v18, s0
	v_cvt_pk_bf16_f32 v2, v2, s0
	s_lshl_b64 s[0:1], s[8:9], 1
	v_lshlrev_b32_e32 v0, 1, v0
	s_add_u32 s0, s3, s0
	v_and_b32_e32 v0, 0x70, v0
	ds_write_b16 v50, v18 offset:51200
	ds_write_b16 v50, v2 offset:54720
	s_addc_u32 s1, s4, s1
	v_lshrrev_b32_e32 v14, 3, v194
	v_add_u32_e32 v15, s2, v0
	s_waitcnt lgkmcnt(0)
	v_lshl_add_u64 v[10:11], s[0:1], 0, v[0:1]
	v_lshl_add_u32 v0, v14, 7, v15
	v_or_b32_e32 v16, 8, v14
	ds_read_b128 v[2:5], v0 offset:51200
	v_lshl_add_u32 v6, v16, 7, v15
	ds_read_b128 v[6:9], v6 offset:51200
	v_lshlrev_b32_e32 v0, 10, v14
	v_lshl_add_u64 v[12:13], v[10:11], 0, v[0:1]
	v_lshlrev_b32_e32 v0, 10, v16
	s_waitcnt lgkmcnt(1)
	global_store_dwordx4 v[12:13], v[2:5], off sc1
	s_add_i32 s45, s45, s24
	s_cmp_lt_i32 s45, s13
	v_lshl_add_u64 v[2:3], v[10:11], 0, v[0:1]
	v_or_b32_e32 v0, 16, v14
	s_waitcnt lgkmcnt(0)
	global_store_dwordx4 v[2:3], v[6:9], off sc1
	v_lshl_add_u32 v2, v0, 7, v15
	v_or_b32_e32 v14, 24, v14
	ds_read_b128 v[2:5], v2 offset:51200
	v_lshl_add_u32 v6, v14, 7, v15
	ds_read_b128 v[6:9], v6 offset:51200
	v_lshlrev_b32_e32 v0, 10, v0
	v_lshl_add_u64 v[12:13], v[10:11], 0, v[0:1]
	v_lshlrev_b32_e32 v0, 10, v14
	s_waitcnt lgkmcnt(1)
	global_store_dwordx4 v[12:13], v[2:5], off sc1
	s_nop 1
	v_lshl_add_u64 v[2:3], v[10:11], 0, v[0:1]
	s_waitcnt lgkmcnt(0)
	global_store_dwordx4 v[2:3], v[6:9], off sc1
	s_waitcnt lgkmcnt(0)
	s_barrier
	s_cbranch_scc0 .LBB0_475

.LBB0_619:
	s_cmp_lg_u32 s9, 0
	s_cselect_b64 vcc, -1, 0
	v_cndmask_b32_e32 v64, 0, v47, vcc
	v_cndmask_b32_e32 v68, 0, v46, vcc
	v_cndmask_b32_e32 v74, 0, v45, vcc
	v_cndmask_b32_e32 v76, 0, v44, vcc
	s_waitcnt vmcnt(1)
	v_lshlrev_b32_e32 v44, 16, v54
	v_and_b32_e32 v45, 0xffff0000, v54
	s_waitcnt vmcnt(0)
	v_lshlrev_b32_e32 v46, 16, v50
	v_and_b32_e32 v47, 0xffff0000, v50
	v_readlane_b32 s0, v254, 37
	v_pk_mul_f32 v[60:61], v[44:45], v[46:47]
	v_lshlrev_b32_e32 v44, 16, v55
	v_and_b32_e32 v45, 0xffff0000, v55
	v_lshlrev_b32_e32 v46, 16, v51
	v_and_b32_e32 v47, 0xffff0000, v51
	v_lshlrev_b64 v[48:49], 2, v[48:49]
	v_readlane_b32 s1, v254, 38
	v_lshlrev_b32_e32 v81, 3, v58
	v_pk_mul_f32 v[58:59], v[44:45], v[46:47]
	v_lshl_add_u64 v[44:45], s[0:1], 0, v[48:49]
	v_readlane_b32 s0, v254, 45
	v_readlane_b32 s1, v254, 46
	v_lshl_add_u64 v[48:49], s[70:71], 0, v[48:49]
	global_load_dwordx4 v[44:47], v[44:45], off
	v_lshl_add_u64 v[66:67], s[0:1], 0, v[52:53]
	global_load_dwordx2 v[66:67], v[66:67], off
	v_readlane_b32 s0, v254, 47
	global_load_dwordx4 v[48:51], v[48:49], off
	v_readlane_b32 s1, v254, 48
	v_lshlrev_b32_e32 v0, 1, v81
	v_lshl_add_u64 v[54:55], s[76:77], 0, v[0:1]
	v_lshl_add_u64 v[52:53], s[0:1], 0, v[52:53]
	global_load_dwordx2 v[82:83], v[52:53], off
	s_lshl_b64 s[0:1], s[4:5], 10
	v_lshl_add_u64 v[52:53], v[54:55], 0, s[0:1]
	global_load_dwordx4 v[52:55], v[52:53], off
	v_mov_b32_e32 v210, v36
	v_mov_b32_e32 v77, v2
	s_mov_b32 s3, 0xf800000
	s_waitcnt vmcnt(4)
	v_mov_b32_e32 v212, v44
	s_waitcnt vmcnt(3)
	v_lshlrev_b32_e32 v87, 16, v66
	v_mul_f32_e32 v73, 0x3d372713, v87
	v_mul_f32_e32 v73, v73, v87
	v_mov_b32_e32 v75, v87
	v_fmac_f32_e32 v75, v73, v75
	v_mul_f32_e32 v73, 0x3f4c422a, v75
	v_add_f32_e32 v73, v73, v73
	v_mul_f32_e32 v73, 0x3fb8aa3b, v73
	v_exp_f32_e32 v73, v73
	s_waitcnt vmcnt(2)
	v_lshlrev_b32_e32 v65, 16, v48
	v_mul_f32_e32 v84, v32, v65
	v_and_b32_e32 v86, 0xffff0000, v48
	v_add_f32_e32 v73, 1.0, v73
	v_rcp_f32_e32 v73, v73
	v_pk_mul_f32 v[86:87], v[210:211], v[86:87]
	s_waitcnt vmcnt(1)
	v_lshlrev_b32_e32 v69, 16, v82
	v_and_b32_e32 v71, 0xffff0000, v82
	v_fma_f32 v85, v73, -2.0, 1.0
	v_pk_add_f32 v[84:85], v[212:213], v[84:85]
	v_lshlrev_b32_e32 v65, 16, v49
	v_mul_f32_e32 v44, v87, v85
	v_add_f32_e32 v73, v86, v84
	v_mov_b32_e32 v84, v4
	v_mov_b32_e32 v85, v8
	v_pk_mul_f32 v[76:77], v[84:85], v[76:77]
	v_mul_f32_e32 v82, v73, v44
	v_fma_f32 v44, v40, v60, v76
	v_add_f32_e32 v44, v44, v77
	v_pk_mov_b32 v[48:49], v[48:49], v[66:67] op_sel:[1,0]
	v_add_f32_e32 v44, v12, v44
	v_and_b32_e32 v49, 0xffff0000, v49
	v_mul_f32_e32 v76, v44, v69
	v_mul_f32_e32 v44, 0x3d372713, v49
	v_mul_f32_e32 v44, v44, v49
	v_mov_b32_e32 v66, v49
	v_fmac_f32_e32 v66, v44, v66
	v_mul_f32_e32 v44, 0x3f4c422a, v66
	v_add_f32_e32 v44, v44, v44
	v_mul_f32_e32 v44, 0x3fb8aa3b, v44
	v_exp_f32_e32 v44, v44
	v_mul_f32_e32 v78, v33, v65
	v_and_b32_e32 v48, 0xffff0000, v48
	v_mov_b32_e32 v210, v37
	v_add_f32_e32 v44, 1.0, v44
	v_rcp_f32_e32 v44, v44
	v_mov_b32_e32 v212, v45
	v_pk_mul_f32 v[48:49], v[210:211], v[48:49]
	v_mov_b32_e32 v75, v3
	v_fma_f32 v79, v44, -2.0, 1.0
	v_pk_add_f32 v[44:45], v[212:213], v[78:79]
	v_lshlrev_b32_e32 v65, 16, v50
	v_mul_f32_e32 v45, v49, v45
	v_add_f32_e32 v44, v48, v44
	v_mul_f32_e32 v48, v44, v45
	v_mov_b32_e32 v44, v5
	v_mov_b32_e32 v45, v9
	v_pk_mul_f32 v[44:45], v[44:45], v[74:75]
	v_mul_f32_e32 v72, v34, v65
	v_fma_f32 v44, v41, v61, v44
	v_add_f32_e32 v44, v44, v45
	v_add_f32_e32 v44, v13, v44
	v_lshlrev_b32_e32 v45, 16, v67
	v_mul_f32_e32 v49, v44, v71
	v_and_b32_e32 v44, 0xffff0000, v50
	v_mul_f32_e32 v50, 0x3d372713, v45
	v_mul_f32_e32 v50, v50, v45
	v_mov_b32_e32 v66, v45
	v_fmac_f32_e32 v66, v50, v66
	v_mul_f32_e32 v50, 0x3f4c422a, v66
	v_add_f32_e32 v50, v50, v50
	v_mul_f32_e32 v50, 0x3fb8aa3b, v50
	v_exp_f32_e32 v50, v50
	v_mov_b32_e32 v210, v38
	v_mov_b32_e32 v212, v46
	v_pk_mul_f32 v[44:45], v[210:211], v[44:45]
	v_add_f32_e32 v50, 1.0, v50
	v_rcp_f32_e32 v50, v50
	v_mov_b32_e32 v69, v56
	v_lshlrev_b32_e32 v65, 16, v51
	v_mul_f32_e32 v70, v35, v65
	v_fma_f32 v73, v50, -2.0, 1.0
	v_pk_add_f32 v[72:73], v[212:213], v[72:73]
	v_lshlrev_b32_e32 v65, 16, v83
	v_mul_f32_e32 v45, v45, v73
	v_add_f32_e32 v44, v44, v72
	v_mul_f32_e32 v50, v44, v45
	v_mov_b32_e32 v44, v6
	v_mov_b32_e32 v45, v10
	v_pk_mul_f32 v[44:45], v[44:45], v[68:69]
	v_mov_b32_e32 v210, v39
	v_fma_f32 v44, v42, v58, v44
	v_add_f32_e32 v44, v44, v45
	v_and_b32_e32 v45, 0xffff0000, v67
	v_add_f32_e32 v44, v14, v44
	v_mul_f32_e32 v46, 0x3d372713, v45
	v_mul_f32_e32 v66, v44, v65
	v_and_b32_e32 v44, 0xffff0000, v51
	v_mul_f32_e32 v46, v46, v45
	v_mov_b32_e32 v51, v45
	v_fmac_f32_e32 v51, v46, v51
	v_mul_f32_e32 v46, 0x3f4c422a, v51
	v_add_f32_e32 v46, v46, v46
	v_mul_f32_e32 v46, 0x3fb8aa3b, v46
	v_exp_f32_e32 v46, v46
	v_mov_b32_e32 v212, v47
	v_pk_mul_f32 v[44:45], v[210:211], v[44:45]
	v_mov_b32_e32 v65, v57
	v_add_f32_e32 v46, 1.0, v46
	v_rcp_f32_e32 v46, v46
	v_and_b32_e32 v83, 0xffff0000, v83
	v_mul_f32_e32 v68, v82, v82
	v_fmac_f32_e32 v68, v48, v48
	v_fma_f32 v71, v46, -2.0, 1.0
	v_pk_add_f32 v[46:47], v[212:213], v[70:71]
	v_fmac_f32_e32 v68, v50, v50
	v_mul_f32_e32 v45, v45, v47
	v_add_f32_e32 v44, v44, v46
	v_mul_f32_e32 v51, v44, v45
	v_mov_b32_e32 v44, v7
	v_mov_b32_e32 v45, v11
	v_pk_mul_f32 v[44:45], v[44:45], v[64:65]
	s_waitcnt vmcnt(0)
	v_lshlrev_b32_e32 v46, 16, v53
	v_fma_f32 v44, v43, v59, v44
	v_add_f32_e32 v44, v44, v45
	v_add_f32_e32 v44, v15, v44
	v_and_b32_e32 v45, 0xffff0000, v52
	v_mul_f32_e32 v64, v44, v83
	v_lshlrev_b32_e32 v44, 16, v52
	v_mul_f32_e32 v65, v45, v45
	v_fmac_f32_e32 v65, v44, v44
	v_and_b32_e32 v47, 0xffff0000, v53
	v_fmac_f32_e32 v65, v46, v46
	v_lshlrev_b32_e32 v52, 16, v54
	v_fmac_f32_e32 v65, v47, v47
	v_and_b32_e32 v53, 0xffff0000, v54
	v_fmac_f32_e32 v65, v52, v52
	v_lshlrev_b32_e32 v54, 16, v55
	v_fmac_f32_e32 v65, v53, v53
	v_and_b32_e32 v55, 0xffff0000, v55
	v_fmac_f32_e32 v65, v54, v54
	v_fmac_f32_e32 v65, v55, v55
	v_fmac_f32_e32 v68, v51, v51
	v_mul_f32_e32 v67, v49, v49
	v_add_f32_dpp v65, v65, v65 quad_perm:[1,0,3,2] row_mask:0xf bank_mask:0xf bound_ctrl:1
	v_add_f32_dpp v68, v68, v68 quad_perm:[1,0,3,2] row_mask:0xf bank_mask:0xf bound_ctrl:1
	v_fmac_f32_e32 v67, v76, v76
	v_add_f32_dpp v65, v65, v65 quad_perm:[2,3,0,1] row_mask:0xf bank_mask:0xf bound_ctrl:1
	v_add_f32_dpp v68, v68, v68 quad_perm:[2,3,0,1] row_mask:0xf bank_mask:0xf bound_ctrl:1
	v_fmac_f32_e32 v67, v66, v66
	v_add_f32_dpp v65, v65, v65 row_half_mirror row_mask:0xf bank_mask:0xf bound_ctrl:1
	v_add_f32_dpp v68, v68, v68 row_half_mirror row_mask:0xf bank_mask:0xf bound_ctrl:1
	v_fmac_f32_e32 v67, v64, v64
	v_add_f32_dpp v65, v65, v65 row_mirror row_mask:0xf bank_mask:0xf bound_ctrl:1
	v_mov_b32_e32 v69, v65
	s_nop 1
	v_permlane16_swap_b32_e32 v65, v69
	v_add_f32_e32 v65, v65, v69
	v_mov_b32_e32 v69, v65
	s_nop 1
	v_permlane32_swap_b32_e32 v65, v69
	v_add_f32_dpp v68, v68, v68 row_mirror row_mask:0xf bank_mask:0xf bound_ctrl:1
	v_add_f32_e32 v65, v65, v69
	v_mov_b32_e32 v69, v68
	s_nop 1
	v_permlane16_swap_b32_e32 v68, v69
	v_add_f32_dpp v67, v67, v67 quad_perm:[1,0,3,2] row_mask:0xf bank_mask:0xf bound_ctrl:1
	v_add_f32_e32 v68, v68, v69
	v_mov_b32_e32 v69, v68
	v_add_f32_dpp v67, v67, v67 quad_perm:[2,3,0,1] row_mask:0xf bank_mask:0xf bound_ctrl:1
	s_nop 0
	v_permlane32_swap_b32_e32 v68, v69
	v_add_f32_dpp v67, v67, v67 row_half_mirror row_mask:0xf bank_mask:0xf bound_ctrl:1
	v_add_f32_e32 v68, v68, v69
	v_fmamk_f32 v65, v65, 0x3b000000, v236
	v_add_f32_dpp v67, v67, v67 row_mirror row_mask:0xf bank_mask:0xf bound_ctrl:1
	v_mov_b32_e32 v69, v67
	s_nop 1
	v_permlane16_swap_b32_e32 v67, v69
	v_add_f32_e32 v67, v67, v69
	v_mov_b32_e32 v69, v67
	s_nop 1
	v_permlane32_swap_b32_e32 v67, v69
	v_add_f32_e32 v67, v67, v69
	v_cmp_gt_f32_e32 vcc, s3, v65
	v_mul_f32_e32 v69, 0x4f800000, v65
	v_fmamk_f32 v68, v68, 0x3b800000, v236
	v_cndmask_b32_e32 v65, v65, v69, vcc
	v_sqrt_f32_e32 v69, v65
	v_fmamk_f32 v67, v67, 0x3b800000, v236
	v_add_u32_e32 v70, -1, v69
	v_fma_f32 v71, -v70, v69, v65
	v_cmp_ge_f32_e64 s[0:1], 0, v71
	v_add_u32_e32 v71, 1, v69
	s_nop 0
	v_cndmask_b32_e64 v70, v69, v70, s[0:1]
	v_fma_f32 v69, -v71, v69, v65
	v_cmp_lt_f32_e64 s[0:1], 0, v69
	s_nop 1
	v_cndmask_b32_e64 v69, v70, v71, s[0:1]
	v_mul_f32_e32 v70, 0x37800000, v69
	v_cndmask_b32_e32 v69, v69, v70, vcc
	v_cmp_class_f32_e32 vcc, v65, v238
	s_nop 1
	v_cndmask_b32_e32 v65, v69, v65, vcc
	v_div_scale_f32 v69, s[0:1], v65, v65, 1.0
	v_rcp_f32_e32 v70, v69
	s_nop 0
	v_fma_f32 v71, -v69, v70, 1.0
	v_fmac_f32_e32 v70, v71, v70
	v_div_scale_f32 v71, vcc, 1.0, v65, 1.0
	v_mul_f32_e32 v72, v71, v70
	v_fma_f32 v73, -v69, v72, v71
	v_fmac_f32_e32 v72, v73, v70
	v_fma_f32 v69, -v69, v72, v71
	v_div_fmas_f32 v69, v69, v70, v72
	v_div_fixup_f32 v65, v69, v65, 1.0
	v_cmp_gt_f32_e32 vcc, s3, v68
	v_mul_f32_e32 v69, 0x4f800000, v68
	v_mul_f32_e32 v44, v65, v44
	v_cndmask_b32_e32 v68, v68, v69, vcc
	v_sqrt_f32_e32 v69, v68
	v_mul_f32_e32 v45, v65, v45
	v_mul_f32_e32 v44, v20, v44
	v_mul_f32_e32 v45, v21, v45
	v_add_u32_e32 v70, -1, v69
	v_fma_f32 v71, -v70, v69, v68
	v_cmp_ge_f32_e64 s[0:1], 0, v71
	v_add_u32_e32 v71, 1, v69
	v_cvt_pk_bf16_f32 v44, v44, v45
	v_mul_f32_e32 v45, v65, v46
	v_cndmask_b32_e64 v70, v69, v70, s[0:1]
	v_fma_f32 v69, -v71, v69, v68
	v_cmp_lt_f32_e64 s[0:1], 0, v69
	v_mul_f32_e32 v46, v65, v47
	v_mul_f32_e32 v45, v22, v45
	v_cndmask_b32_e64 v69, v70, v71, s[0:1]
	v_mul_f32_e32 v70, 0x37800000, v69
	v_cndmask_b32_e32 v69, v69, v70, vcc
	v_cmp_class_f32_e32 vcc, v68, v238
	v_mul_f32_e32 v46, v23, v46
	v_cvt_pk_bf16_f32 v45, v45, v46
	v_mul_f32_e32 v46, v65, v52
	v_cndmask_b32_e32 v68, v69, v68, vcc
	v_div_scale_f32 v69, s[0:1], v68, v68, 1.0
	v_rcp_f32_e32 v70, v69
	v_mul_f32_e32 v47, v65, v53
	v_mul_f32_e32 v46, v16, v46
	v_mul_f32_e32 v47, v17, v47
	v_fma_f32 v71, -v69, v70, 1.0
	v_fmac_f32_e32 v70, v71, v70
	v_div_scale_f32 v71, vcc, 1.0, v68, 1.0
	v_mul_f32_e32 v72, v71, v70
	v_fma_f32 v73, -v69, v72, v71
	v_fmac_f32_e32 v72, v73, v70
	v_fma_f32 v69, -v69, v72, v71
	v_div_fmas_f32 v69, v69, v70, v72
	v_div_fixup_f32 v68, v69, v68, 1.0
	v_cmp_gt_f32_e32 vcc, s3, v67
	v_mul_f32_e32 v69, 0x4f800000, v67
	v_cvt_pk_bf16_f32 v46, v46, v47
	v_mul_f32_e32 v47, v65, v54
	v_cndmask_b32_e32 v67, v67, v69, vcc
	v_sqrt_f32_e32 v69, v67
	v_mul_f32_e32 v47, v18, v47
	v_mul_f32_e32 v52, v65, v55
	v_mul_f32_e32 v52, v19, v52
	v_add_u32_e32 v70, -1, v69
	v_fma_f32 v71, -v70, v69, v67
	v_cmp_ge_f32_e64 s[0:1], 0, v71
	v_add_u32_e32 v71, 1, v69
	v_cvt_pk_bf16_f32 v47, v47, v52
	s_nop 0
	v_cndmask_b32_e64 v70, v69, v70, s[0:1]
	v_fma_f32 v69, -v71, v69, v67
	v_cmp_lt_f32_e64 s[0:1], 0, v69
	s_nop 1
	v_cndmask_b32_e64 v69, v70, v71, s[0:1]
	v_mul_f32_e32 v70, 0x37800000, v69
	v_cndmask_b32_e32 v69, v69, v70, vcc
	v_cmp_class_f32_e32 vcc, v67, v238
	s_nop 1
	v_cndmask_b32_e32 v67, v69, v67, vcc
	v_div_scale_f32 v69, s[0:1], v67, v67, 1.0
	v_rcp_f32_e32 v70, v69
	s_lshl_b64 s[0:1], s[4:5], 11
	s_add_u32 s0, s48, s0
	s_addc_u32 s1, s49, s1
	v_fma_f32 v71, -v69, v70, 1.0
	v_fmac_f32_e32 v70, v71, v70
	v_div_scale_f32 v71, vcc, 1.0, v67, 1.0
	v_mul_f32_e32 v72, v71, v70
	v_fma_f32 v73, -v69, v72, v71
	global_store_dwordx4 v0, v[44:47], s[0:1] sc1
	v_mul_f32_e32 v0, v82, v68
	v_fmac_f32_e32 v72, v73, v70
	v_mul_f32_e32 v44, v48, v68
	v_mul_f32_e32 v0, v24, v0
	v_mul_f32_e32 v44, v25, v44
	v_fma_f32 v69, -v69, v72, v71
	v_cvt_pk_bf16_f32 v44, v0, v44
	v_mul_f32_e32 v0, v50, v68
	v_mul_f32_e32 v45, v51, v68
	v_div_fmas_f32 v69, v69, v70, v72
	v_mul_f32_e32 v0, v26, v0
	v_mul_f32_e32 v45, v27, v45
	v_div_fixup_f32 v67, v69, v67, 1.0
	v_cvt_pk_bf16_f32 v45, v0, v45
	v_lshlrev_b32_e32 v0, 1, v63
	global_store_dwordx2 v0, v[44:45], s[0:1] offset:1024
	v_mul_f32_e32 v44, v76, v67
	v_mul_f32_e32 v45, v49, v67
	v_mul_f32_e32 v44, v28, v44
	v_mul_f32_e32 v45, v29, v45
	v_cvt_pk_bf16_f32 v44, v44, v45
	v_mul_f32_e32 v45, v66, v67
	v_mul_f32_e32 v45, v30, v45
	v_mul_f32_e32 v46, v64, v67
	s_cmp_ge_i32 s6, s8
	v_mul_f32_e32 v46, v31, v46
	v_cvt_pk_bf16_f32 v45, v45, v46
	global_store_dwordx2 v0, v[44:45], s[0:1] offset:1536
	s_cbranch_scc1 .LBB0_632
	v_readlane_b32 s0, v254, 43
	v_mov_b32_e32 v63, v1
	v_readlane_b32 s1, v254, 44
	s_ashr_i32 s7, s6, 31
	s_add_i32 s3, s4, 0xffff0001
	v_lshl_add_u64 v[62:63], s[0:1], 0, v[62:63]
	s_lshl_b64 s[0:1], s[6:7], 9
	v_mov_b32_e32 v65, s1
	v_or_b32_e32 v64, s0, v81
	s_lshl_b64 s[0:1], s[6:7], 11
	v_or_b32_e32 v66, s0, v81
	s_add_u32 s0, s0, 0x16000000
	v_lshlrev_b32_e32 v0, 4, v80
	v_mov_b32_e32 v67, s1
	s_addc_u32 s1, s1, 0
	v_and_b32_e32 v0, 0x3f0, v0
	v_or_b32_e32 v68, s0, v0
	v_mov_b32_e32 v69, s1
	s_lshl_b64 s[0:1], s[6:7], 10
	v_or_b32_e32 v70, s0, v0
	s_add_i32 s0, s4, 2
	v_mov_b32_e32 v71, s1
	s_ashr_i32 s1, s0, 31
	s_lshl_b64 s[0:1], s[0:1], 9
	v_readlane_b32 s12, v253, 20
	v_mov_b32_e32 v52, v40
	v_mov_b32_e32 v53, v8
	v_mov_b32_e32 v8, v41
	v_mov_b32_e32 v54, v42
	v_mov_b32_e32 v55, v10
	v_mov_b32_e32 v10, v43
	v_mov_b32_e32 v73, s1
	v_or_b32_e32 v72, s0, v81
	v_readlane_b32 s14, v253, 22
	v_readlane_b32 s15, v253, 23
	s_mov_b64 s[10:11], 0x200
	v_readlane_b32 s13, v253, 21
	s_branch .LBB0_622
.LBB0_621:
	v_lshl_add_u64 v[46:47], s[14:15], 0, v[70:71]
	v_add_co_u32_e32 v40, vcc, 0x2ec00000, v46
	s_waitcnt vmcnt(0)
	v_mov_b32_e32 v210, v36
	v_addc_co_u32_e32 v41, vcc, 0, v47, vcc
	v_add_co_u32_e32 v48, vcc, 0x32e00000, v46
	global_load_dwordx4 v[40:43], v[40:41], off
	s_nop 0
	v_addc_co_u32_e32 v49, vcc, 0, v47, vcc
	global_load_dwordx4 v[48:51], v[48:49], off
	v_add_co_u32_e32 v82, vcc, 0x26800000, v44
	s_mov_b32 s4, 0xf800000
	s_nop 0
	v_addc_co_u32_e32 v83, vcc, 0, v45, vcc
	global_load_dwordx2 v[84:85], v[82:83], off
	v_add_co_u32_e32 v44, vcc, 0x28900000, v44
	v_lshl_add_u64 v[64:65], v[64:65], 0, s[10:11]
	s_nop 0
	v_addc_co_u32_e32 v45, vcc, 0, v45, vcc
	global_load_dwordx2 v[88:89], v[44:45], off
	v_add_co_u32_e32 v44, vcc, 0x37000000, v46
	v_lshl_add_u64 v[72:73], v[72:73], 0, s[10:11]
	s_nop 0
	v_addc_co_u32_e32 v45, vcc, 0, v47, vcc
	global_load_dwordx4 v[44:47], v[44:45], off
	s_waitcnt vmcnt(4)
	v_mov_b32_e32 v212, v40
	s_waitcnt vmcnt(3)
	v_lshlrev_b32_e32 v0, 16, v48
	v_mul_f32_e32 v90, v32, v0
	v_lshlrev_b32_e32 v0, 16, v49
	v_mul_f32_e32 v92, v33, v0
	v_lshlrev_b32_e32 v0, 16, v50
	v_mul_f32_e32 v86, v34, v0
	v_lshlrev_b32_e32 v0, 16, v51
	s_waitcnt vmcnt(2)
	v_lshlrev_b32_e32 v95, 16, v84
	v_mul_f32_e32 v82, v35, v0
	v_mul_f32_e32 v0, 0x3d372713, v95
	v_mul_f32_e32 v0, v0, v95
	v_mov_b32_e32 v78, v95
	v_fmac_f32_e32 v78, v0, v78
	v_mul_f32_e32 v0, 0x3f4c422a, v78
	v_add_f32_e32 v0, v0, v0
	v_mul_f32_e32 v0, 0x3fb8aa3b, v0
	v_exp_f32_e32 v0, v0
	v_and_b32_e32 v94, 0xffff0000, v48
	v_pk_mul_f32 v[94:95], v[210:211], v[94:95]
	v_mov_b32_e32 v78, v2
	v_add_f32_e32 v0, 1.0, v0
	v_rcp_f32_e32 v0, v0
	v_pk_mov_b32 v[48:49], v[48:49], v[84:85] op_sel:[1,0]
	s_waitcnt vmcnt(1)
	v_lshlrev_b32_e32 v76, 16, v88
	v_and_b32_e32 v49, 0xffff0000, v49
	v_fma_f32 v91, v0, -2.0, 1.0
	v_pk_add_f32 v[90:91], v[212:213], v[90:91]
	v_and_b32_e32 v48, 0xffff0000, v48
	v_mul_f32_e32 v0, v95, v91
	v_add_f32_e32 v40, v94, v90
	v_pk_mul_f32 v[90:91], v[52:53], v[78:79]
	v_mul_f32_e32 v0, v40, v0
	v_fma_f32 v40, v4, v60, v90
	v_add_f32_e32 v40, v40, v91
	v_add_f32_e32 v40, v12, v40
	v_mul_f32_e32 v60, v40, v76
	v_mul_f32_e32 v40, 0x3d372713, v49
	v_mul_f32_e32 v40, v40, v49
	v_mov_b32_e32 v76, v49
	v_fmac_f32_e32 v76, v40, v76
	v_mul_f32_e32 v40, 0x3f4c422a, v76
	v_add_f32_e32 v40, v40, v40
	v_mul_f32_e32 v40, 0x3fb8aa3b, v40
	v_exp_f32_e32 v40, v40
	v_mov_b32_e32 v210, v37
	v_mov_b32_e32 v212, v41
	v_pk_mul_f32 v[48:49], v[210:211], v[48:49]
	v_add_f32_e32 v40, 1.0, v40
	v_rcp_f32_e32 v40, v40
	v_mov_b32_e32 v76, v3
	v_and_b32_e32 v80, 0xffff0000, v88
	v_mov_b32_e32 v210, v38
	v_fma_f32 v93, v40, -2.0, 1.0
	v_pk_add_f32 v[40:41], v[212:213], v[92:93]
	v_mov_b32_e32 v212, v42
	v_mul_f32_e32 v41, v49, v41
	v_add_f32_e32 v40, v48, v40
	v_mul_f32_e32 v48, v40, v41
	v_pk_mul_f32 v[40:41], v[8:9], v[76:77]
	v_lshlrev_b32_e32 v74, 16, v89
	v_fma_f32 v40, v5, v61, v40
	v_add_f32_e32 v40, v40, v41
	v_add_f32_e32 v40, v13, v40
	v_lshlrev_b32_e32 v41, 16, v85
	v_mul_f32_e32 v49, v40, v80
	v_and_b32_e32 v40, 0xffff0000, v50
	v_mul_f32_e32 v50, 0x3d372713, v41
	v_mul_f32_e32 v50, v50, v41
	v_mov_b32_e32 v61, v41
	v_fmac_f32_e32 v61, v50, v61
	v_mul_f32_e32 v50, 0x3f4c422a, v61
	v_add_f32_e32 v50, v50, v50
	v_mul_f32_e32 v50, 0x3fb8aa3b, v50
	v_exp_f32_e32 v50, v50
	v_pk_mul_f32 v[40:41], v[210:211], v[40:41]
	v_mov_b32_e32 v80, v56
	v_mov_b32_e32 v210, v39
	v_add_f32_e32 v50, 1.0, v50
	v_rcp_f32_e32 v50, v50
	v_and_b32_e32 v88, 0xffff0000, v89
	v_mul_f32_e32 v76, v0, v0
	v_fmac_f32_e32 v76, v48, v48
	v_fma_f32 v87, v50, -2.0, 1.0
	v_pk_add_f32 v[86:87], v[212:213], v[86:87]
	v_mov_b32_e32 v212, v43
	v_mul_f32_e32 v41, v41, v87
	v_add_f32_e32 v40, v40, v86
	v_mul_f32_e32 v50, v40, v41
	v_pk_mul_f32 v[40:41], v[54:55], v[80:81]
	v_fmac_f32_e32 v76, v50, v50
	v_fma_f32 v40, v6, v58, v40
	v_add_f32_e32 v40, v40, v41
	v_and_b32_e32 v41, 0xffff0000, v85
	v_add_f32_e32 v40, v14, v40
	v_mul_f32_e32 v42, 0x3d372713, v41
	v_mul_f32_e32 v58, v40, v74
	v_and_b32_e32 v40, 0xffff0000, v51
	v_mul_f32_e32 v42, v42, v41
	v_mov_b32_e32 v51, v41
	v_fmac_f32_e32 v51, v42, v51
	v_mul_f32_e32 v42, 0x3f4c422a, v51
	v_add_f32_e32 v42, v42, v42
	v_mul_f32_e32 v42, 0x3fb8aa3b, v42
	v_exp_f32_e32 v42, v42
	v_pk_mul_f32 v[40:41], v[210:211], v[40:41]
	v_mov_b32_e32 v74, v57
	v_add_f32_e32 v42, 1.0, v42
	v_rcp_f32_e32 v42, v42
	s_nop 0
	v_fma_f32 v83, v42, -2.0, 1.0
	v_pk_add_f32 v[42:43], v[212:213], v[82:83]
	s_nop 0
	v_mul_f32_e32 v41, v41, v43
	v_add_f32_e32 v40, v40, v42
	v_mul_f32_e32 v51, v40, v41
	v_pk_mul_f32 v[40:41], v[10:11], v[74:75]
	s_waitcnt vmcnt(0)
	v_lshlrev_b32_e32 v42, 16, v45
	v_fma_f32 v40, v7, v59, v40
	v_add_f32_e32 v40, v40, v41
	v_add_f32_e32 v40, v15, v40
	v_and_b32_e32 v41, 0xffff0000, v44
	v_mul_f32_e32 v59, v40, v88
	v_lshlrev_b32_e32 v40, 16, v44
	v_mul_f32_e32 v61, v41, v41
	v_fmac_f32_e32 v61, v40, v40
	v_and_b32_e32 v43, 0xffff0000, v45
	v_fmac_f32_e32 v61, v42, v42
	v_lshlrev_b32_e32 v44, 16, v46
	v_fmac_f32_e32 v61, v43, v43
	v_and_b32_e32 v45, 0xffff0000, v46
	v_fmac_f32_e32 v61, v44, v44
	v_lshlrev_b32_e32 v46, 16, v47
	v_fmac_f32_e32 v61, v45, v45
	v_and_b32_e32 v47, 0xffff0000, v47
	v_fmac_f32_e32 v61, v46, v46
	v_fmac_f32_e32 v61, v47, v47
	v_fmac_f32_e32 v76, v51, v51
	v_mul_f32_e32 v74, v49, v49
	v_add_f32_dpp v61, v61, v61 quad_perm:[1,0,3,2] row_mask:0xf bank_mask:0xf bound_ctrl:1
	v_add_f32_dpp v76, v76, v76 quad_perm:[1,0,3,2] row_mask:0xf bank_mask:0xf bound_ctrl:1
	v_fmac_f32_e32 v74, v60, v60
	v_add_f32_dpp v61, v61, v61 quad_perm:[2,3,0,1] row_mask:0xf bank_mask:0xf bound_ctrl:1
	v_add_f32_dpp v76, v76, v76 quad_perm:[2,3,0,1] row_mask:0xf bank_mask:0xf bound_ctrl:1
	v_fmac_f32_e32 v74, v58, v58
	v_add_f32_dpp v61, v61, v61 row_half_mirror row_mask:0xf bank_mask:0xf bound_ctrl:1
	v_add_f32_dpp v76, v76, v76 row_half_mirror row_mask:0xf bank_mask:0xf bound_ctrl:1
	v_fmac_f32_e32 v74, v59, v59
	v_add_f32_dpp v61, v61, v61 row_mirror row_mask:0xf bank_mask:0xf bound_ctrl:1
	v_mov_b32_e32 v78, v61
	s_nop 1
	v_permlane16_swap_b32_e32 v61, v78
	v_add_f32_e32 v61, v61, v78
	v_mov_b32_e32 v78, v61
	s_nop 1
	v_permlane32_swap_b32_e32 v61, v78
	v_add_f32_dpp v76, v76, v76 row_mirror row_mask:0xf bank_mask:0xf bound_ctrl:1
	v_add_f32_e32 v61, v61, v78
	v_mov_b32_e32 v78, v76
	s_nop 1
	v_permlane16_swap_b32_e32 v76, v78
	v_add_f32_dpp v74, v74, v74 quad_perm:[1,0,3,2] row_mask:0xf bank_mask:0xf bound_ctrl:1
	v_add_f32_e32 v76, v76, v78
	v_mov_b32_e32 v78, v76
	v_add_f32_dpp v74, v74, v74 quad_perm:[2,3,0,1] row_mask:0xf bank_mask:0xf bound_ctrl:1
	s_nop 0
	v_permlane32_swap_b32_e32 v76, v78
	v_add_f32_dpp v74, v74, v74 row_half_mirror row_mask:0xf bank_mask:0xf bound_ctrl:1
	v_add_f32_e32 v76, v76, v78
	v_fmamk_f32 v61, v61, 0x3b000000, v236
	v_add_f32_dpp v74, v74, v74 row_mirror row_mask:0xf bank_mask:0xf bound_ctrl:1
	v_mov_b32_e32 v78, v74
	s_nop 1
	v_permlane16_swap_b32_e32 v74, v78
	v_add_f32_e32 v74, v74, v78
	v_mov_b32_e32 v78, v74
	s_nop 1
	v_permlane32_swap_b32_e32 v74, v78
	v_add_f32_e32 v74, v74, v78
	v_cmp_gt_f32_e32 vcc, s4, v61
	v_mul_f32_e32 v78, 0x4f800000, v61
	v_fmamk_f32 v76, v76, 0x3b800000, v236
	v_cndmask_b32_e32 v61, v61, v78, vcc
	v_sqrt_f32_e32 v78, v61
	v_fmamk_f32 v74, v74, 0x3b800000, v236
	v_add_u32_e32 v80, -1, v78
	v_fma_f32 v82, -v80, v78, v61
	v_cmp_ge_f32_e64 s[0:1], 0, v82
	v_add_u32_e32 v82, 1, v78
	s_nop 0
	v_cndmask_b32_e64 v80, v78, v80, s[0:1]
	v_fma_f32 v78, -v82, v78, v61
	v_cmp_lt_f32_e64 s[0:1], 0, v78
	s_nop 1
	v_cndmask_b32_e64 v78, v80, v82, s[0:1]
	v_mul_f32_e32 v80, 0x37800000, v78
	v_cndmask_b32_e32 v78, v78, v80, vcc
	v_cmp_class_f32_e32 vcc, v61, v238
	s_nop 1
	v_cndmask_b32_e32 v61, v78, v61, vcc
	v_div_scale_f32 v78, s[0:1], v61, v61, 1.0
	v_rcp_f32_e32 v80, v78
	s_nop 0
	v_fma_f32 v82, -v78, v80, 1.0
	v_fmac_f32_e32 v80, v82, v80
	v_div_scale_f32 v82, vcc, 1.0, v61, 1.0
	v_mul_f32_e32 v83, v82, v80
	v_fma_f32 v84, -v78, v83, v82
	v_fmac_f32_e32 v83, v84, v80
	v_fma_f32 v78, -v78, v83, v82
	v_div_fmas_f32 v78, v78, v80, v83
	v_div_fixup_f32 v61, v78, v61, 1.0
	v_cmp_gt_f32_e32 vcc, s4, v76
	v_mul_f32_e32 v78, 0x4f800000, v76
	v_mul_f32_e32 v40, v61, v40
	v_cndmask_b32_e32 v76, v76, v78, vcc
	v_sqrt_f32_e32 v78, v76
	v_mul_f32_e32 v41, v61, v41
	v_mul_f32_e32 v40, v20, v40
	v_mul_f32_e32 v41, v21, v41
	v_add_u32_e32 v80, -1, v78
	v_fma_f32 v82, -v80, v78, v76
	v_cmp_ge_f32_e64 s[0:1], 0, v82
	v_add_u32_e32 v82, 1, v78
	v_cvt_pk_bf16_f32 v40, v40, v41
	v_mul_f32_e32 v41, v61, v42
	v_cndmask_b32_e64 v80, v78, v80, s[0:1]
	v_fma_f32 v78, -v82, v78, v76
	v_cmp_lt_f32_e64 s[0:1], 0, v78
	v_mul_f32_e32 v42, v61, v43
	v_mul_f32_e32 v41, v22, v41
	v_cndmask_b32_e64 v78, v80, v82, s[0:1]
	v_mul_f32_e32 v80, 0x37800000, v78
	v_cndmask_b32_e32 v78, v78, v80, vcc
	v_cmp_class_f32_e32 vcc, v76, v238
	v_mul_f32_e32 v42, v23, v42
	v_cvt_pk_bf16_f32 v41, v41, v42
	v_mul_f32_e32 v42, v61, v44
	v_cndmask_b32_e32 v76, v78, v76, vcc
	v_div_scale_f32 v78, s[0:1], v76, v76, 1.0
	v_rcp_f32_e32 v80, v78
	v_mul_f32_e32 v43, v61, v45
	v_mul_f32_e32 v42, v16, v42
	v_mul_f32_e32 v43, v17, v43
	v_fma_f32 v82, -v78, v80, 1.0
	v_fmac_f32_e32 v80, v82, v80
	v_div_scale_f32 v82, vcc, 1.0, v76, 1.0
	v_mul_f32_e32 v83, v82, v80
	v_fma_f32 v84, -v78, v83, v82
	v_fmac_f32_e32 v83, v84, v80
	v_fma_f32 v78, -v78, v83, v82
	v_div_fmas_f32 v78, v78, v80, v83
	v_div_fixup_f32 v76, v78, v76, 1.0
	v_cmp_gt_f32_e32 vcc, s4, v74
	v_mul_f32_e32 v78, 0x4f800000, v74
	v_cvt_pk_bf16_f32 v42, v42, v43
	v_mul_f32_e32 v43, v61, v46
	v_cndmask_b32_e32 v74, v74, v78, vcc
	v_sqrt_f32_e32 v78, v74
	v_mul_f32_e32 v44, v61, v47
	v_mul_f32_e32 v43, v18, v43
	v_mul_f32_e32 v44, v19, v44
	v_add_u32_e32 v80, -1, v78
	v_fma_f32 v82, -v80, v78, v74
	v_cmp_ge_f32_e64 s[0:1], 0, v82
	v_add_u32_e32 v82, 1, v78
	v_cvt_pk_bf16_f32 v43, v43, v44
	v_lshl_add_u64 v[44:45], s[14:15], 0, v[68:69]
	v_cndmask_b32_e64 v80, v78, v80, s[0:1]
	v_fma_f32 v78, -v82, v78, v74
	v_cmp_lt_f32_e64 s[0:1], 0, v78
	global_store_dwordx4 v[44:45], v[40:43], off sc1
	v_mul_f32_e32 v0, v0, v76
	v_cndmask_b32_e64 v78, v80, v82, s[0:1]
	v_mul_f32_e32 v80, 0x37800000, v78
	v_cndmask_b32_e32 v78, v78, v80, vcc
	v_cmp_class_f32_e32 vcc, v74, v238
	v_mul_f32_e32 v40, v48, v76
	v_mul_f32_e32 v0, v24, v0
	v_cndmask_b32_e32 v74, v78, v74, vcc
	v_div_scale_f32 v78, s[0:1], v74, v74, 1.0
	v_rcp_f32_e32 v80, v78
	v_mul_f32_e32 v40, v25, v40
	v_lshl_add_u64 v[42:43], s[14:15], 0, v[66:67]
	s_mov_b32 s0, 0x16000000
	v_fma_f32 v82, -v78, v80, 1.0
	v_fmac_f32_e32 v80, v82, v80
	v_div_scale_f32 v82, vcc, 1.0, v74, 1.0
	v_mul_f32_e32 v83, v82, v80
	v_fma_f32 v84, -v78, v83, v82
	v_fmac_f32_e32 v83, v84, v80
	v_fma_f32 v78, -v78, v83, v82
	v_div_fmas_f32 v78, v78, v80, v83
	v_cvt_pk_bf16_f32 v40, v0, v40
	v_mul_f32_e32 v0, v50, v76
	v_mul_f32_e32 v41, v51, v76
	v_add_co_u32_e32 v42, vcc, s0, v42
	v_div_fixup_f32 v74, v78, v74, 1.0
	v_mul_f32_e32 v0, v26, v0
	v_mul_f32_e32 v41, v27, v41
	v_addc_co_u32_e32 v43, vcc, 0, v43, vcc
	v_cvt_pk_bf16_f32 v41, v0, v41
	global_store_dwordx2 v[42:43], v[40:41], off offset:1024
	v_mul_f32_e32 v0, v60, v74
	v_mul_f32_e32 v40, v49, v74
	s_mov_b64 s[0:1], 0x800
	v_mul_f32_e32 v0, v28, v0
	v_mul_f32_e32 v40, v29, v40
	v_mul_f32_e32 v41, v59, v74
	s_add_i32 s4, s3, 1
	s_add_i32 s3, s3, 0x10001
	v_lshl_add_u64 v[66:67], v[66:67], 0, s[0:1]
	v_lshl_add_u64 v[68:69], v[68:69], 0, s[0:1]
	s_mov_b64 s[0:1], 0x400
	v_cvt_pk_bf16_f32 v40, v0, v40
	v_mul_f32_e32 v0, v58, v74
	v_mul_f32_e32 v41, v31, v41
	v_lshl_add_u64 v[70:71], v[70:71], 0, s[0:1]
	s_cmp_lt_i32 s3, s8
	s_mov_b32 s3, s4
	v_mov_b32_e32 v60, v2
	v_mov_b32_e32 v61, v3
	v_mov_b32_e32 v58, v56
	v_mov_b32_e32 v59, v57
	v_mov_b32_e32 v2, v79
	v_mov_b32_e32 v3, v77
	v_mov_b32_e32 v56, v81
	v_mov_b32_e32 v57, v75
	v_mul_f32_e32 v0, v30, v0
	v_cvt_pk_bf16_f32 v41, v0, v41
	global_store_dwordx2 v[42:43], v[40:41], off offset:1536
	s_cbranch_scc0 .LBB0_632

.LBB0_720:
	s_waitcnt vmcnt(0)
	v_pk_mul_f32 v[144:145], s[44:45], v[144:145]
	v_pk_mul_f32 v[142:143], s[10:11], v[142:143]
	v_pk_mul_f32 v[140:141], s[44:45], v[140:141]
	v_pk_mul_f32 v[138:139], s[10:11], v[138:139]
	v_pk_mul_f32 v[136:137], s[44:45], v[136:137]
	v_pk_mul_f32 v[134:135], s[10:11], v[134:135]
	v_pk_mul_f32 v[132:133], s[44:45], v[132:133]
	v_pk_mul_f32 v[130:131], s[10:11], v[130:131]
	v_pk_fma_f32 v[128:129], v[128:129], v[144:145], v[148:149]
	v_pk_fma_f32 v[126:127], v[126:127], v[142:143], v[146:147]
	v_pk_fma_f32 v[146:147], v[124:125], v[140:141], v[156:157]
	v_pk_fma_f32 v[124:125], v[122:123], v[138:139], v[154:155]
	v_cvt_pk_bf16_f32 v122, v126, v127
	v_cvt_pk_bf16_f32 v123, v128, v129
	v_pk_fma_f32 v[120:121], v[120:121], v[136:137], v[152:153]
	v_cvt_pk_bf16_f32 v124, v124, v125
	v_cvt_pk_bf16_f32 v125, v146, v147
	global_store_dwordx4 v[232:233], v[122:125], off sc1
	v_pk_fma_f32 v[118:119], v[118:119], v[134:135], v[150:151]
	v_pk_fma_f32 v[104:105], v[104:105], v[136:137], v[164:165]
	v_pk_fma_f32 v[122:123], v[112:113], v[132:133], v[160:161]
	v_pk_fma_f32 v[112:113], v[110:111], v[130:131], v[158:159]
	v_cvt_pk_bf16_f32 v110, v118, v119
	v_cvt_pk_bf16_f32 v111, v120, v121
	v_pk_fma_f32 v[102:103], v[102:103], v[134:135], v[162:163]
	v_cvt_pk_bf16_f32 v112, v112, v113
	v_cvt_pk_bf16_f32 v113, v122, v123
	global_store_dwordx4 v[232:233], v[110:113], off offset:256 sc1
	v_pk_fma_f32 v[88:89], v[88:89], v[136:137], v[180:181]
	v_pk_fma_f32 v[86:87], v[86:87], v[134:135], v[178:179]
	v_pk_fma_f32 v[110:111], v[116:117], v[144:145], v[168:169]
	v_pk_fma_f32 v[112:113], v[114:115], v[142:143], v[166:167]
	v_pk_fma_f32 v[114:115], v[108:109], v[140:141], v[176:177]
	v_pk_fma_f32 v[108:109], v[106:107], v[138:139], v[174:175]
	v_cvt_pk_bf16_f32 v106, v112, v113
	v_cvt_pk_bf16_f32 v107, v110, v111
	v_add_co_u32_e32 v110, vcc, s91, v232
	v_cvt_pk_bf16_f32 v108, v108, v109
	v_cvt_pk_bf16_f32 v109, v114, v115
	v_add_u32_e32 v146, 0x80, v230
	s_nop 0
	v_addc_co_u32_e32 v111, vcc, 0, v233, vcc
	global_store_dwordx4 v[110:111], v[106:109], off sc1
	v_pk_fma_f32 v[72:73], v[72:73], v[136:137], v[196:197]
	v_pk_fma_f32 v[70:71], v[70:71], v[134:135], v[194:195]
	v_pk_fma_f32 v[106:107], v[96:97], v[132:133], v[172:173]
	v_pk_fma_f32 v[96:97], v[94:95], v[130:131], v[170:171]
	v_cvt_pk_bf16_f32 v94, v102, v103
	v_cvt_pk_bf16_f32 v95, v104, v105
	v_ashrrev_i32_e32 v147, 31, v146
	v_cvt_pk_bf16_f32 v96, v96, v97
	v_cvt_pk_bf16_f32 v97, v106, v107
	global_store_dwordx4 v[110:111], v[94:97], off offset:256 sc1
	s_nop 1
	v_pk_fma_f32 v[94:95], v[100:101], v[144:145], v[184:185]
	v_pk_fma_f32 v[96:97], v[98:99], v[142:143], v[182:183]
	v_pk_fma_f32 v[98:99], v[92:93], v[140:141], v[192:193]
	v_pk_fma_f32 v[92:93], v[90:91], v[138:139], v[190:191]
	v_cvt_pk_bf16_f32 v90, v96, v97
	v_cvt_pk_bf16_f32 v91, v94, v95
	v_add_co_u32_e32 v94, vcc, s33, v232
	v_cvt_pk_bf16_f32 v92, v92, v93
	v_cvt_pk_bf16_f32 v93, v98, v99
	s_nop 1
	v_addc_co_u32_e32 v95, vcc, 0, v233, vcc
	global_store_dwordx4 v[94:95], v[90:93], off sc1
	s_nop 1
	v_pk_fma_f32 v[90:91], v[80:81], v[132:133], v[188:189]
	v_pk_fma_f32 v[80:81], v[78:79], v[130:131], v[186:187]
	v_cvt_pk_bf16_f32 v78, v86, v87
	v_cvt_pk_bf16_f32 v79, v88, v89
	s_nop 0
	v_cvt_pk_bf16_f32 v80, v80, v81
	v_cvt_pk_bf16_f32 v81, v90, v91
	global_store_dwordx4 v[94:95], v[78:81], off offset:256 sc1
	s_nop 1
	v_pk_fma_f32 v[78:79], v[84:85], v[144:145], v[200:201]
	v_pk_fma_f32 v[80:81], v[82:83], v[142:143], v[198:199]
	v_pk_fma_f32 v[82:83], v[76:77], v[140:141], v[208:209]
	v_pk_fma_f32 v[76:77], v[74:75], v[138:139], v[206:207]
	v_cvt_pk_bf16_f32 v74, v80, v81
	v_cvt_pk_bf16_f32 v75, v78, v79
	v_add_co_u32_e32 v78, vcc, s90, v232
	v_cvt_pk_bf16_f32 v76, v76, v77
	v_cvt_pk_bf16_f32 v77, v82, v83
	s_nop 1
	v_addc_co_u32_e32 v79, vcc, 0, v233, vcc
	global_store_dwordx4 v[78:79], v[74:77], off sc1
	s_and_b64 vcc, exec, s[0:1]
	s_mov_b64 s[0:1], -1
	v_pk_fma_f32 v[74:75], v[68:69], v[132:133], v[204:205]
	v_pk_fma_f32 v[68:69], v[66:67], v[130:131], v[202:203]
	v_cvt_pk_bf16_f32 v66, v70, v71
	v_cvt_pk_bf16_f32 v67, v72, v73
	s_nop 0
	v_cvt_pk_bf16_f32 v68, v68, v69
	v_cvt_pk_bf16_f32 v69, v74, v75
	global_store_dwordx4 v[78:79], v[66:69], off offset:256 sc1
	s_cbranch_vccnz .LBB0_726
	s_andn2_b64 vcc, exec, s[68:69]
	s_cbranch_vccnz .LBB0_723
	v_readlane_b32 s68, v253, 3
	v_lshlrev_b64 v[66:67], 12, v[230:231]
	v_readlane_b32 s72, v253, 7
	v_readlane_b32 s73, v253, 8
	s_mov_b32 s0, 0xf0080000
	v_readlane_b32 s74, v253, 9
	v_readlane_b32 s75, v253, 10
	v_lshl_add_u64 v[66:67], s[72:73], 0, v[66:67]
	s_mov_b32 s1, -1
	s_mov_b64 s[74:75], 0x10000
	v_lshl_add_u64 v[66:67], v[66:67], 0, s[0:1]
	s_mov_b64 s[0:1], 0
	v_readlane_b32 s69, v253, 4
	v_readlane_b32 s70, v253, 5
	v_readlane_b32 s71, v253, 6
	v_readlane_b32 s76, v253, 11
	v_readlane_b32 s77, v253, 12
	v_readlane_b32 s78, v253, 13
	v_readlane_b32 s79, v253, 14
	v_readlane_b32 s80, v253, 15
	v_readlane_b32 s81, v253, 16
	v_readlane_b32 s82, v253, 17
	v_readlane_b32 s83, v253, 18

.LBB0_728:
	s_waitcnt vmcnt(14)
	v_pk_fma_f32 v[64:65], v[64:65], v[144:145], v[76:77]
	v_pk_fma_f32 v[62:63], v[62:63], v[142:143], v[74:75]
	v_pk_fma_f32 v[74:75], v[60:61], v[140:141], v[84:85]
	v_pk_fma_f32 v[60:61], v[58:59], v[138:139], v[82:83]
	v_cvt_pk_bf16_f32 v58, v62, v63
	v_cvt_pk_bf16_f32 v59, v64, v65
	s_waitcnt vmcnt(12)
	v_pk_fma_f32 v[56:57], v[56:57], v[136:137], v[68:69]
	v_cvt_pk_bf16_f32 v60, v60, v61
	v_cvt_pk_bf16_f32 v61, v74, v75
	global_store_dwordx4 v[146:147], v[58:61], off sc1
	v_pk_fma_f32 v[54:55], v[54:55], v[134:135], v[66:67]
	s_waitcnt vmcnt(10)
	v_pk_fma_f32 v[40:41], v[40:41], v[136:137], v[80:81]
	v_pk_fma_f32 v[58:59], v[48:49], v[132:133], v[72:73]
	v_pk_fma_f32 v[48:49], v[46:47], v[130:131], v[70:71]
	v_cvt_pk_bf16_f32 v46, v54, v55
	v_cvt_pk_bf16_f32 v47, v56, v57
	v_pk_fma_f32 v[38:39], v[38:39], v[134:135], v[78:79]
	v_cvt_pk_bf16_f32 v48, v48, v49
	v_cvt_pk_bf16_f32 v49, v58, v59
	global_store_dwordx4 v[146:147], v[46:49], off offset:256 sc1
	s_waitcnt vmcnt(7)
	v_pk_fma_f32 v[24:25], v[24:25], v[136:137], v[100:101]
	v_pk_fma_f32 v[22:23], v[22:23], v[134:135], v[98:99]
	v_pk_fma_f32 v[46:47], v[52:53], v[144:145], v[88:89]
	v_pk_fma_f32 v[48:49], v[50:51], v[142:143], v[86:87]
	v_pk_fma_f32 v[50:51], v[44:45], v[140:141], v[96:97]
	v_pk_fma_f32 v[44:45], v[42:43], v[138:139], v[94:95]
	v_cvt_pk_bf16_f32 v42, v48, v49
	v_cvt_pk_bf16_f32 v43, v46, v47
	v_add_co_u32_e32 v46, vcc, s91, v146
	v_cvt_pk_bf16_f32 v44, v44, v45
	v_cvt_pk_bf16_f32 v45, v50, v51
	s_mov_b64 s[0:1], -1
	s_nop 0
	v_addc_co_u32_e32 v47, vcc, 0, v147, vcc
	global_store_dwordx4 v[46:47], v[42:45], off sc1
	s_waitcnt vmcnt(4)
	v_pk_fma_f32 v[8:9], v[8:9], v[136:137], v[116:117]
	v_pk_fma_f32 v[6:7], v[6:7], v[134:135], v[114:115]
	v_pk_fma_f32 v[42:43], v[32:33], v[132:133], v[92:93]
	v_pk_fma_f32 v[32:33], v[30:31], v[130:131], v[90:91]
	v_cvt_pk_bf16_f32 v30, v38, v39
	v_cvt_pk_bf16_f32 v31, v40, v41
	s_nop 0
	v_cvt_pk_bf16_f32 v32, v32, v33
	v_cvt_pk_bf16_f32 v33, v42, v43
	global_store_dwordx4 v[46:47], v[30:33], off offset:256 sc1
	s_nop 1
	v_pk_fma_f32 v[30:31], v[36:37], v[144:145], v[104:105]
	v_pk_fma_f32 v[32:33], v[34:35], v[142:143], v[102:103]
	v_pk_fma_f32 v[34:35], v[28:29], v[140:141], v[112:113]
	v_pk_fma_f32 v[28:29], v[26:27], v[138:139], v[110:111]
	v_cvt_pk_bf16_f32 v26, v32, v33
	v_cvt_pk_bf16_f32 v27, v30, v31
	v_add_co_u32_e32 v30, vcc, s33, v146
	v_cvt_pk_bf16_f32 v28, v28, v29
	v_cvt_pk_bf16_f32 v29, v34, v35
	s_nop 1
	v_addc_co_u32_e32 v31, vcc, 0, v147, vcc
	global_store_dwordx4 v[30:31], v[26:29], off sc1
	s_nop 1
	v_pk_fma_f32 v[26:27], v[16:17], v[132:133], v[108:109]
	v_pk_fma_f32 v[16:17], v[14:15], v[130:131], v[106:107]
	v_cvt_pk_bf16_f32 v14, v22, v23
	v_cvt_pk_bf16_f32 v15, v24, v25
	s_nop 0
	v_cvt_pk_bf16_f32 v16, v16, v17
	v_cvt_pk_bf16_f32 v17, v26, v27
	global_store_dwordx4 v[30:31], v[14:17], off offset:256 sc1
	s_nop 1
	v_pk_fma_f32 v[14:15], v[20:21], v[144:145], v[120:121]
	v_pk_fma_f32 v[16:17], v[18:19], v[142:143], v[118:119]
	v_pk_fma_f32 v[18:19], v[12:13], v[140:141], v[128:129]
	v_pk_fma_f32 v[12:13], v[10:11], v[138:139], v[126:127]
	v_cvt_pk_bf16_f32 v10, v16, v17
	v_cvt_pk_bf16_f32 v11, v14, v15
	v_add_co_u32_e32 v14, vcc, s90, v146
	v_cvt_pk_bf16_f32 v12, v12, v13
	v_cvt_pk_bf16_f32 v13, v18, v19
	s_nop 1
	v_addc_co_u32_e32 v15, vcc, 0, v147, vcc
	global_store_dwordx4 v[14:15], v[10:13], off sc1
	s_and_b64 vcc, exec, s[4:5]
	s_waitcnt vmcnt(7)
	v_pk_fma_f32 v[10:11], v[4:5], v[132:133], v[124:125]
	v_pk_fma_f32 v[4:5], v[2:3], v[130:131], v[122:123]
	v_cvt_pk_bf16_f32 v2, v6, v7
	v_cvt_pk_bf16_f32 v3, v8, v9
	s_nop 0
	v_cvt_pk_bf16_f32 v4, v4, v5
	v_cvt_pk_bf16_f32 v5, v10, v11
	global_store_dwordx4 v[14:15], v[2:5], off offset:256 sc1
	s_cbranch_vccnz .LBB0_694
	s_andn2_b64 vcc, exec, s[26:27]
	s_cbranch_vccnz .LBB0_693
	s_barrier
	s_branch .LBB0_693
